# all s_setprio removed from the four GEMM K-loops (on top of snake order, SGPR-base DMA addressing, attention vmcnt relaxation)
# speedup vs baseline: 1.0123x; 1.0080x over previous
; template <class Epi, class Sched, bool ALIGN_EPI = false, bool SP2 = false>
; __device__ __forceinline__ void gemm_phase(PG8_LAS unsigned char* lds, const Gemm g, const Sched& S, const Epi& E) {
;     ...
;         if constexpr (Epi::PEEL) {
;             const char* a1 = cA + kstepA; const char* a2 = cA + 2 * kstepA; const char* b2 = cB + 2 * kstepB; const char* a3 = a2 + kstepA; const char* b3 = b2 + kstepB;
;             PG8_ITER(8);
;         }
.LBB0_160:
	s_ashr_i32 s55, s54, 31
	s_lshl_b64 s[2:3], s[54:55], 15
	v_readlane_b32 s8, v255, 15
	s_add_u32 s12, s8, s2
	v_readlane_b32 s2, v255, 16
	s_addc_u32 s13, s2, s3
	s_ashr_i32 s49, s48, 31
	s_lshl_b64 s[2:3], s[48:49], 19
	v_readlane_b32 s8, v255, 29
	s_add_u32 s46, s8, s2
	v_readlane_b32 s2, v255, 40
	s_addc_u32 s47, s2, s3
	s_add_u32 s28, s24, 0x800000
	s_addc_u32 s29, s25, 0
	s_add_u32 s42, s24, 0xc00000
	s_addc_u32 s43, s25, 0
	s_add_i32 s55, 0, 0x10000
	s_and_b64 s[2:3], s[30:31], exec
	s_cselect_b32 s27, s13, s25
	s_cselect_b32 s44, s12, s24
	s_add_i32 vcc_hi, 0, 0x14000
	v_add_u32_e32 v142, s55, v97
	v_add_u32_e32 v143, vcc_hi, v97
	ds_read_b128 v[0:3], v142
	ds_read_b128 v[4:7], v142 offset:1024
	ds_read_b128 v[8:11], v142 offset:2048
	ds_read_b128 v[12:15], v142 offset:3072
	ds_read_b128 v[16:19], v143
	s_waitcnt lgkmcnt(0)
	ds_read_b128 v[20:23], v143 offset:1024
	ds_read_b128 v[24:27], v143 offset:2048
	ds_read_b128 v[28:31], v143 offset:3072
	v_writelane_b32 v255, s30, 33
	s_and_b64 s[2:3], s[30:31], exec
	s_cselect_b32 s45, s47, s1
	v_writelane_b32 v255, s31, 34
	s_cselect_b32 s49, s46, s0
	s_add_u32 s2, s24, 0x404000
	s_addc_u32 s3, s25, 0
	s_add_i32 s50, s22, 0xc000
	s_mov_b32 m0, s50
	s_add_i32 s51, s22, 0xe000
	ds_read_b128 v[32:35], v161
	ds_read_b128 v[36:39], v161 offset:1024
	ds_read_b128 v[40:43], v161 offset:2048
	ds_read_b128 v[44:47], v161 offset:3072
	ds_read_b128 v[48:51], v161 offset:4096
	ds_read_b128 v[52:55], v161 offset:5120
	ds_read_b128 v[56:59], v161 offset:6144
	ds_read_b128 v[60:63], v161 offset:7168
	global_load_lds_dwordx4 v130, s[2:3]
	s_mov_b32 m0, s51
	s_nop 0
	global_load_lds_dwordx4 v134, s[2:3]
	s_waitcnt vmcnt(8)
	s_waitcnt lgkmcnt(0)
	s_barrier
	s_waitcnt lgkmcnt(0)
	v_mfma_f32_16x16x32_bf16 v[64:67], v[0:3], v[32:35], 0
	v_mfma_f32_16x16x32_bf16 v[68:71], v[8:11], v[32:35], 0
	v_mfma_f32_16x16x32_bf16 v[72:75], v[0:3], v[40:43], 0
	v_mfma_f32_16x16x32_bf16 v[76:79], v[8:11], v[40:43], 0
	v_mfma_f32_16x16x32_bf16 v[80:83], v[0:3], v[48:51], 0
	v_mfma_f32_16x16x32_bf16 v[84:87], v[8:11], v[48:51], 0
	v_mfma_f32_16x16x32_bf16 v[88:91], v[0:3], v[56:59], 0
	v_mfma_f32_16x16x32_bf16 v[92:95], v[8:11], v[56:59], 0
	v_mfma_f32_16x16x32_bf16 v[64:67], v[4:7], v[36:39], v[64:67]
	v_mfma_f32_16x16x32_bf16 v[68:71], v[12:15], v[36:39], v[68:71]
	v_mfma_f32_16x16x32_bf16 v[72:75], v[4:7], v[44:47], v[72:75]
	v_mfma_f32_16x16x32_bf16 v[76:79], v[12:15], v[44:47], v[76:79]
	v_mfma_f32_16x16x32_bf16 v[80:83], v[4:7], v[52:55], v[80:83]
	v_mfma_f32_16x16x32_bf16 v[84:87], v[12:15], v[52:55], v[84:87]
	v_mfma_f32_16x16x32_bf16 v[88:91], v[4:7], v[60:63], v[88:91]
	v_mfma_f32_16x16x32_bf16 v[98:101], v[12:15], v[60:63], v[92:95]
	v_mfma_f32_16x16x32_bf16 v[92:95], v[16:19], v[32:35], 0
	v_mfma_f32_16x16x32_bf16 v[32:35], v[24:27], v[32:35], 0
	v_mfma_f32_16x16x32_bf16 v[106:109], v[20:23], v[36:39], v[92:95]
	v_mfma_f32_16x16x32_bf16 v[32:35], v[28:31], v[36:39], v[32:35]
	v_mfma_f32_16x16x32_bf16 v[36:39], v[16:19], v[40:43], 0
	v_mfma_f32_16x16x32_bf16 v[40:43], v[24:27], v[40:43], 0
	v_mfma_f32_16x16x32_bf16 v[36:39], v[20:23], v[44:47], v[36:39]
	v_mfma_f32_16x16x32_bf16 v[40:43], v[28:31], v[44:47], v[40:43]
	v_mfma_f32_16x16x32_bf16 v[44:47], v[16:19], v[48:51], 0
	v_mfma_f32_16x16x32_bf16 v[48:51], v[24:27], v[48:51], 0
	v_mfma_f32_16x16x32_bf16 v[44:47], v[20:23], v[52:55], v[44:47]
	v_mfma_f32_16x16x32_bf16 v[48:51], v[28:31], v[52:55], v[48:51]
	v_mfma_f32_16x16x32_bf16 v[52:55], v[16:19], v[56:59], 0
	v_mfma_f32_16x16x32_bf16 v[56:59], v[24:27], v[56:59], 0
	v_mfma_f32_16x16x32_bf16 v[52:55], v[20:23], v[60:63], v[52:55]
	v_mfma_f32_16x16x32_bf16 v[56:59], v[28:31], v[60:63], v[56:59]
	s_barrier
	v_lshl_add_u64 v[158:159], s[0:1], 0, v[132:133]
	s_mov_b64 s[2:3], 0x100
	s_add_i32 s55, s55, s10
	v_lshl_add_u64 v[144:145], v[158:159], 0, s[2:3]
	s_mov_b32 m0, s55
	v_lshl_add_u64 v[178:179], s[0:1], 0, v[136:137]
	s_add_i32 vcc_lo, s55, 0x2000
	ds_read_b128 v[60:63], v161 offset:16384
	ds_read_b128 v[92:95], v161 offset:17408
	ds_read_b128 v[102:105], v161 offset:18432
	ds_read_b128 v[110:113], v161 offset:19456
	ds_read_b128 v[114:117], v161 offset:20480
	ds_read_b128 v[118:121], v161 offset:21504
	ds_read_b128 v[122:125], v161 offset:22528
	ds_read_b128 v[126:129], v161 offset:23552
	global_load_lds_dwordx4 v[144:145], off
	v_lshl_add_u64 v[144:145], v[178:179], 0, s[2:3]
	s_add_u32 s2, s0, 0x40100
	s_mov_b32 m0, vcc_lo
	s_addc_u32 s3, s1, 0
	s_add_i32 vcc_hi, vcc_hi, s10
	global_load_lds_dwordx4 v[144:145], off
	s_mov_b32 m0, vcc_hi
	s_add_i32 s56, vcc_hi, 0x2000
	global_load_lds_dwordx4 v132, s[2:3]
	s_mov_b32 m0, s56
	s_nop 0
	global_load_lds_dwordx4 v136, s[2:3]
	s_mov_b32 m0, s22
	s_nop 0
	global_load_lds_dwordx4 v130, s[28:29]
	s_mov_b32 m0, s23
	s_nop 0
	global_load_lds_dwordx4 v134, s[28:29]
	s_waitcnt vmcnt(8)
	s_waitcnt lgkmcnt(0)
	s_barrier
; template <class Epi, class Sched, bool ALIGN_EPI = false, bool SP2 = false>
; __device__ __forceinline__ void gemm_phase(PG8_LAS unsigned char* lds, const Gemm g, const Sched& S, const Epi& E) {
;     ...
;         if constexpr (Epi::PEEL) {
;             const char* a1 = cA + kstepA; const char* a2 = cA + 2 * kstepA; const char* b2 = cB + 2 * kstepB; const char* a3 = a2 + kstepA; const char* b3 = b2 + kstepB;
;             PG8_ITER(8);
;         }
	s_waitcnt lgkmcnt(0)
	v_mfma_f32_16x16x32_bf16 v[144:147], v[0:3], v[60:63], 0
	v_mfma_f32_16x16x32_bf16 v[154:157], v[0:3], v[102:105], 0
	v_mfma_f32_16x16x32_bf16 v[166:169], v[0:3], v[114:117], 0
	v_mfma_f32_16x16x32_bf16 v[0:3], v[0:3], v[122:125], 0
	v_mfma_f32_16x16x32_bf16 v[146:149], v[4:7], v[92:95], v[144:147]
	v_mfma_f32_16x16x32_bf16 v[154:157], v[4:7], v[110:113], v[154:157]
	v_mfma_f32_16x16x32_bf16 v[166:169], v[4:7], v[118:121], v[166:169]
	v_mfma_f32_16x16x32_bf16 v[0:3], v[4:7], v[126:129], v[0:3]
	v_mfma_f32_16x16x32_bf16 v[4:7], v[8:11], v[122:125], 0
	v_mfma_f32_16x16x32_bf16 v[150:153], v[8:11], v[60:63], 0
	v_mfma_f32_16x16x32_bf16 v[162:165], v[8:11], v[102:105], 0
	v_mfma_f32_16x16x32_bf16 v[170:173], v[8:11], v[114:117], 0
	v_mfma_f32_16x16x32_bf16 v[4:7], v[12:15], v[126:129], v[4:7]
	v_mfma_f32_16x16x32_bf16 v[150:153], v[12:15], v[92:95], v[150:153]
	v_mfma_f32_16x16x32_bf16 v[162:165], v[12:15], v[110:113], v[162:165]
	v_mfma_f32_16x16x32_bf16 v[170:173], v[12:15], v[118:121], v[170:173]
	v_mfma_f32_16x16x32_bf16 v[12:15], v[24:27], v[60:63], 0
	v_mfma_f32_16x16x32_bf16 v[174:177], v[28:31], v[92:95], v[12:15]
	v_mfma_f32_16x16x32_bf16 v[12:15], v[16:19], v[102:105], 0
	v_mfma_f32_16x16x32_bf16 v[180:183], v[20:23], v[110:113], v[12:15]
	v_mfma_f32_16x16x32_bf16 v[12:15], v[24:27], v[102:105], 0
	v_mfma_f32_16x16x32_bf16 v[184:187], v[28:31], v[110:113], v[12:15]
	v_mfma_f32_16x16x32_bf16 v[12:15], v[16:19], v[114:117], 0
	v_mfma_f32_16x16x32_bf16 v[188:191], v[20:23], v[118:121], v[12:15]
	v_mfma_f32_16x16x32_bf16 v[12:15], v[24:27], v[114:117], 0
	v_mfma_f32_16x16x32_bf16 v[8:11], v[16:19], v[60:63], 0
	v_mfma_f32_16x16x32_bf16 v[192:195], v[28:31], v[118:121], v[12:15]
	v_mfma_f32_16x16x32_bf16 v[12:15], v[16:19], v[122:125], 0
	v_mfma_f32_16x16x32_bf16 v[8:11], v[20:23], v[92:95], v[8:11]
	v_mfma_f32_16x16x32_bf16 v[196:199], v[20:23], v[126:129], v[12:15]
	v_mfma_f32_16x16x32_bf16 v[12:15], v[24:27], v[122:125], 0
	v_mfma_f32_16x16x32_bf16 v[200:203], v[28:31], v[126:129], v[12:15]
	s_barrier
	s_add_i32 s30, 0, 0x18000
	s_add_i32 s57, 0, 0x1c000
	v_add_u32_e32 v144, s30, v97
	v_add_u32_e32 v145, s57, v97
	s_nop 0
	ds_read_b128 v[12:15], v144
	ds_read_b128 v[16:19], v144 offset:1024
	ds_read_b128 v[24:27], v144 offset:2048
	ds_read_b128 v[204:207], v144 offset:3072
	ds_read_b128 v[208:211], v145
	ds_read_b128 v[212:215], v145 offset:1024
	ds_read_b128 v[216:219], v145 offset:2048
	ds_read_b128 v[220:223], v145 offset:3072
	s_add_u32 s2, s24, 0x804000
	s_addc_u32 s3, s25, 0
	s_mov_b32 m0, s39
	ds_read_b128 v[20:23], v161 offset:32768
	ds_read_b128 v[28:31], v161 offset:33792
	ds_read_b128 v[60:63], v161 offset:34816
	ds_read_b128 v[224:227], v161 offset:35840
	ds_read_b128 v[228:231], v161 offset:36864
	ds_read_b128 v[234:237], v161 offset:37888
	ds_read_b128 v[238:241], v161 offset:38912
	ds_read_b128 v[242:245], v161 offset:39936
	global_load_lds_dwordx4 v130, s[2:3]
	s_mov_b32 m0, s52
	s_nop 0
	global_load_lds_dwordx4 v134, s[2:3]
	s_waitcnt vmcnt(8)
	s_waitcnt lgkmcnt(0)
	s_barrier
	s_waitcnt lgkmcnt(0)
	v_mfma_f32_16x16x32_bf16 v[64:67], v[12:15], v[20:23], v[64:67]
	v_mfma_f32_16x16x32_bf16 v[126:129], v[16:19], v[28:31], v[64:67]
	v_mfma_f32_16x16x32_bf16 v[64:67], v[24:27], v[20:23], v[68:71]
	v_mfma_f32_16x16x32_bf16 v[118:121], v[204:207], v[28:31], v[64:67]
	v_mfma_f32_16x16x32_bf16 v[64:67], v[12:15], v[60:63], v[72:75]
	v_mfma_f32_16x16x32_bf16 v[110:113], v[16:19], v[224:227], v[64:67]
	v_mfma_f32_16x16x32_bf16 v[64:67], v[24:27], v[60:63], v[76:79]
	v_mfma_f32_16x16x32_bf16 v[102:105], v[204:207], v[224:227], v[64:67]
	v_mfma_f32_16x16x32_bf16 v[64:67], v[12:15], v[228:231], v[80:83]
	v_mfma_f32_16x16x32_bf16 v[92:95], v[16:19], v[234:237], v[64:67]
	v_mfma_f32_16x16x32_bf16 v[64:67], v[24:27], v[228:231], v[84:87]
	v_mfma_f32_16x16x32_bf16 v[84:87], v[204:207], v[234:237], v[64:67]
	v_mfma_f32_16x16x32_bf16 v[64:67], v[12:15], v[238:241], v[88:91]
	v_mfma_f32_16x16x32_bf16 v[76:79], v[16:19], v[242:245], v[64:67]
	v_mfma_f32_16x16x32_bf16 v[64:67], v[24:27], v[238:241], v[98:101]
	v_mfma_f32_16x16x32_bf16 v[68:71], v[204:207], v[242:245], v[64:67]
	v_mfma_f32_16x16x32_bf16 v[64:67], v[208:211], v[20:23], v[106:109]
	v_mfma_f32_16x16x32_bf16 v[20:23], v[216:219], v[20:23], v[32:35]
	v_mfma_f32_16x16x32_bf16 v[114:117], v[220:223], v[28:31], v[20:23]
	v_mfma_f32_16x16x32_bf16 v[20:23], v[208:211], v[60:63], v[36:39]
	v_mfma_f32_16x16x32_bf16 v[106:109], v[212:215], v[224:227], v[20:23]
	v_mfma_f32_16x16x32_bf16 v[20:23], v[216:219], v[60:63], v[40:43]
	v_mfma_f32_16x16x32_bf16 v[98:101], v[220:223], v[224:227], v[20:23]
	v_mfma_f32_16x16x32_bf16 v[20:23], v[208:211], v[228:231], v[44:47]
	v_mfma_f32_16x16x32_bf16 v[88:91], v[212:215], v[234:237], v[20:23]
	v_mfma_f32_16x16x32_bf16 v[20:23], v[216:219], v[228:231], v[48:51]
	v_mfma_f32_16x16x32_bf16 v[80:83], v[220:223], v[234:237], v[20:23]
	v_mfma_f32_16x16x32_bf16 v[20:23], v[208:211], v[238:241], v[52:55]
	v_mfma_f32_16x16x32_bf16 v[72:75], v[212:215], v[242:245], v[20:23]
	v_mfma_f32_16x16x32_bf16 v[20:23], v[216:219], v[238:241], v[56:59]
	v_mfma_f32_16x16x32_bf16 v[122:125], v[212:215], v[28:31], v[64:67]
	v_mfma_f32_16x16x32_bf16 v[64:67], v[220:223], v[242:245], v[20:23]
	s_barrier
; template <class Epi, class Sched, bool ALIGN_EPI = false, bool SP2 = false>
; __device__ __forceinline__ void gemm_phase(PG8_LAS unsigned char* lds, const Gemm g, const Sched& S, const Epi& E) {
;     ...
;         if constexpr (Epi::PEEL) {
;             const char* a1 = cA + kstepA; const char* a2 = cA + 2 * kstepA; const char* b2 = cB + 2 * kstepB; const char* a3 = a2 + kstepA; const char* b3 = b2 + kstepB;
;             PG8_ITER(8);
;         }
;         for (int t = (Epi::PEEL ? 2 : 0); t < nt; t += 2) {
;             const bool last = (t == nt - 2);
;             const char* a1 = cA + (size_t)(t + 1) * kstepA;
;             const char* a2 = last ? nA : cA + (size_t)(t + 2) * kstepA; const char* b2 = last ? nB : cB + (size_t)(t + 2) * kstepB;
;             const char* a3 = a2 + kstepA; const char* b3 = b2 + kstepB;
;             PG8_ITER(8);
;         }
	s_mov_b64 s[2:3], 0x180
	s_add_i32 s30, s30, s10
	s_nop 1
	v_lshl_add_u64 v[20:21], v[158:159], 0, s[2:3]
	s_mov_b32 m0, s30
	s_add_i32 s31, s30, 0x2000
	ds_read_b128 v[32:35], v161 offset:49152
	ds_read_b128 v[40:43], v161 offset:50176
	ds_read_b128 v[224:227], v161 offset:51200
	ds_read_b128 v[228:231], v161 offset:52224
	ds_read_b128 v[234:237], v161 offset:53248
	ds_read_b128 v[238:241], v161 offset:54272
	ds_read_b128 v[242:245], v161 offset:55296
	ds_read_b128 v[246:249], v161 offset:56320
	global_load_lds_dwordx4 v[20:21], off
	v_lshl_add_u64 v[20:21], v[178:179], 0, s[2:3]
	s_add_u32 s2, s0, 0x40180
	s_mov_b32 m0, s31
	s_addc_u32 s3, s1, 0
	s_add_i32 s57, s57, s10
	global_load_lds_dwordx4 v[20:21], off
	s_mov_b32 m0, s57
	s_add_i32 s96, s57, 0x2000
	global_load_lds_dwordx4 v132, s[2:3]
	s_mov_b32 m0, s96
	s_nop 0
	global_load_lds_dwordx4 v136, s[2:3]
	s_mov_b32 m0, s11
	s_nop 0
	global_load_lds_dwordx4 v130, s[42:43]
	s_mov_b32 m0, s19
	s_nop 0
	global_load_lds_dwordx4 v134, s[42:43]
	s_waitcnt vmcnt(8)
	s_waitcnt lgkmcnt(0)
	s_barrier
	s_waitcnt lgkmcnt(0)
	v_mfma_f32_16x16x32_bf16 v[20:23], v[12:15], v[32:35], v[146:149]
	v_mfma_f32_16x16x32_bf16 v[60:63], v[16:19], v[40:43], v[20:23]
	v_mfma_f32_16x16x32_bf16 v[20:23], v[24:27], v[32:35], v[150:153]
	v_mfma_f32_16x16x32_bf16 v[52:55], v[204:207], v[40:43], v[20:23]
	v_mfma_f32_16x16x32_bf16 v[20:23], v[12:15], v[224:227], v[154:157]
	v_mfma_f32_16x16x32_bf16 v[44:47], v[16:19], v[228:231], v[20:23]
	v_mfma_f32_16x16x32_bf16 v[20:23], v[24:27], v[224:227], v[162:165]
	v_mfma_f32_16x16x32_bf16 v[36:39], v[204:207], v[228:231], v[20:23]
	v_mfma_f32_16x16x32_bf16 v[20:23], v[12:15], v[234:237], v[166:169]
	v_mfma_f32_16x16x32_bf16 v[0:3], v[12:15], v[242:245], v[0:3]
	v_mfma_f32_16x16x32_bf16 v[28:31], v[16:19], v[238:241], v[20:23]
	v_mfma_f32_16x16x32_bf16 v[20:23], v[24:27], v[234:237], v[170:173]
	v_mfma_f32_16x16x32_bf16 v[12:15], v[16:19], v[246:249], v[0:3]
	v_mfma_f32_16x16x32_bf16 v[0:3], v[24:27], v[242:245], v[4:7]
	v_mfma_f32_16x16x32_bf16 v[20:23], v[204:207], v[238:241], v[20:23]
	v_mfma_f32_16x16x32_bf16 v[4:7], v[204:207], v[246:249], v[0:3]
	v_mfma_f32_16x16x32_bf16 v[0:3], v[208:211], v[32:35], v[8:11]
	v_mfma_f32_16x16x32_bf16 v[56:59], v[212:215], v[40:43], v[0:3]
	v_mfma_f32_16x16x32_bf16 v[0:3], v[216:219], v[32:35], v[174:177]
	v_mfma_f32_16x16x32_bf16 v[48:51], v[220:223], v[40:43], v[0:3]
	v_mfma_f32_16x16x32_bf16 v[0:3], v[208:211], v[224:227], v[180:183]
	v_mfma_f32_16x16x32_bf16 v[40:43], v[212:215], v[228:231], v[0:3]
	v_mfma_f32_16x16x32_bf16 v[0:3], v[216:219], v[224:227], v[184:187]
	v_mfma_f32_16x16x32_bf16 v[32:35], v[220:223], v[228:231], v[0:3]
	v_mfma_f32_16x16x32_bf16 v[0:3], v[208:211], v[234:237], v[188:191]
	v_mfma_f32_16x16x32_bf16 v[24:27], v[212:215], v[238:241], v[0:3]
	v_mfma_f32_16x16x32_bf16 v[0:3], v[216:219], v[234:237], v[192:195]
	v_mfma_f32_16x16x32_bf16 v[16:19], v[220:223], v[238:241], v[0:3]
	v_mfma_f32_16x16x32_bf16 v[0:3], v[208:211], v[242:245], v[196:199]
	v_mfma_f32_16x16x32_bf16 v[8:11], v[212:215], v[246:249], v[0:3]
	v_mfma_f32_16x16x32_bf16 v[0:3], v[216:219], v[242:245], v[200:203]
	v_mfma_f32_16x16x32_bf16 v[0:3], v[220:223], v[246:249], v[0:3]
	s_barrier
	s_add_u32 s3, s0, 0x200
	s_addc_u32 s2, s1, 0
	s_add_u32 s0, s24, 0xc04000
	s_addc_u32 s1, s25, 0
	s_mov_b32 s18, 0
.LBB0_161:
	ds_read_b128 v[146:149], v142
	ds_read_b128 v[150:153], v142 offset:1024
	ds_read_b128 v[154:157], v142 offset:2048
	ds_read_b128 v[162:165], v142 offset:3072
	ds_read_b128 v[166:169], v143
	ds_read_b128 v[170:173], v143 offset:1024
	ds_read_b128 v[174:177], v143 offset:2048
	ds_read_b128 v[180:183], v143 offset:3072
	s_add_u32 s8, s0, 0x3fc000
	s_addc_u32 s9, s1, 0
	s_cmp_eq_u32 s18, 12
	s_cselect_b32 s28, s44, s8
	s_cselect_b32 s29, s27, s9
	s_cselect_b32 s42, s49, s3
	s_cselect_b32 s43, s45, s2
	s_add_u32 s24, s28, 0x400000
	s_addc_u32 s25, s29, 0
	s_mov_b32 m0, s50
	ds_read_b128 v[184:187], v161
	ds_read_b128 v[188:191], v161 offset:1024
	ds_read_b128 v[192:195], v161 offset:2048
	ds_read_b128 v[196:199], v161 offset:3072
	ds_read_b128 v[200:203], v161 offset:4096
	ds_read_b128 v[204:207], v161 offset:5120
	ds_read_b128 v[208:211], v161 offset:6144
	ds_read_b128 v[212:215], v161 offset:7168
	global_load_lds_dwordx4 v140, s[0:1]
	s_mov_b32 m0, s51
	s_nop 0
	global_load_lds_dwordx4 v138, s[0:1]
	s_waitcnt vmcnt(8)
	s_waitcnt lgkmcnt(0)
	s_barrier
	s_waitcnt lgkmcnt(0)
	v_mfma_f32_16x16x32_bf16 v[126:129], v[146:149], v[184:187], v[126:129]
	v_mfma_f32_16x16x32_bf16 v[118:121], v[154:157], v[184:187], v[118:121]
	v_mfma_f32_16x16x32_bf16 v[102:105], v[154:157], v[192:195], v[102:105]
	v_mfma_f32_16x16x32_bf16 v[110:113], v[146:149], v[192:195], v[110:113]
	v_mfma_f32_16x16x32_bf16 v[92:95], v[146:149], v[200:203], v[92:95]
	v_mfma_f32_16x16x32_bf16 v[84:87], v[154:157], v[200:203], v[84:87]
	v_mfma_f32_16x16x32_bf16 v[68:71], v[154:157], v[208:211], v[68:71]
	v_mfma_f32_16x16x32_bf16 v[76:79], v[146:149], v[208:211], v[76:79]
	v_mfma_f32_16x16x32_bf16 v[126:129], v[150:153], v[188:191], v[126:129]
	v_mfma_f32_16x16x32_bf16 v[118:121], v[162:165], v[188:191], v[118:121]
	v_mfma_f32_16x16x32_bf16 v[102:105], v[162:165], v[196:199], v[102:105]
	v_mfma_f32_16x16x32_bf16 v[110:113], v[150:153], v[196:199], v[110:113]
	v_mfma_f32_16x16x32_bf16 v[92:95], v[150:153], v[204:207], v[92:95]
	v_mfma_f32_16x16x32_bf16 v[84:87], v[162:165], v[204:207], v[84:87]
	v_mfma_f32_16x16x32_bf16 v[68:71], v[162:165], v[212:215], v[68:71]
	v_mfma_f32_16x16x32_bf16 v[76:79], v[150:153], v[212:215], v[76:79]
	v_mfma_f32_16x16x32_bf16 v[122:125], v[166:169], v[184:187], v[122:125]
	v_mfma_f32_16x16x32_bf16 v[114:117], v[174:177], v[184:187], v[114:117]
	v_mfma_f32_16x16x32_bf16 v[98:101], v[174:177], v[192:195], v[98:101]
	v_mfma_f32_16x16x32_bf16 v[106:109], v[166:169], v[192:195], v[106:109]
	v_mfma_f32_16x16x32_bf16 v[88:91], v[166:169], v[200:203], v[88:91]
	v_mfma_f32_16x16x32_bf16 v[80:83], v[174:177], v[200:203], v[80:83]
	v_mfma_f32_16x16x32_bf16 v[64:67], v[174:177], v[208:211], v[64:67]
	v_mfma_f32_16x16x32_bf16 v[72:75], v[166:169], v[208:211], v[72:75]
	v_mfma_f32_16x16x32_bf16 v[122:125], v[170:173], v[188:191], v[122:125]
	v_mfma_f32_16x16x32_bf16 v[114:117], v[180:183], v[188:191], v[114:117]
	v_mfma_f32_16x16x32_bf16 v[98:101], v[180:183], v[196:199], v[98:101]
	v_mfma_f32_16x16x32_bf16 v[106:109], v[170:173], v[196:199], v[106:109]
	v_mfma_f32_16x16x32_bf16 v[88:91], v[170:173], v[204:207], v[88:91]
	v_mfma_f32_16x16x32_bf16 v[80:83], v[180:183], v[204:207], v[80:83]
	v_mfma_f32_16x16x32_bf16 v[64:67], v[180:183], v[212:215], v[64:67]
	v_mfma_f32_16x16x32_bf16 v[72:75], v[170:173], v[212:215], v[72:75]
	s_barrier
	s_mov_b32 m0, s55
	s_add_u32 s8, s42, 0x40000
	ds_read_b128 v[184:187], v161 offset:16384
	ds_read_b128 v[188:191], v161 offset:17408
	ds_read_b128 v[192:195], v161 offset:18432
	ds_read_b128 v[196:199], v161 offset:19456
	ds_read_b128 v[200:203], v161 offset:20480
	ds_read_b128 v[204:207], v161 offset:21504
	ds_read_b128 v[208:211], v161 offset:22528
	ds_read_b128 v[212:215], v161 offset:23552
	global_load_lds_dwordx4 v132, s[42:43]
	s_mov_b32 m0, vcc_lo
	s_addc_u32 s9, s43, 0
	global_load_lds_dwordx4 v136, s[42:43]
	s_mov_b32 m0, vcc_hi
	s_nop 0
	global_load_lds_dwordx4 v132, s[8:9]
	s_mov_b32 m0, s56
	s_nop 0
	global_load_lds_dwordx4 v136, s[8:9]
	s_mov_b32 m0, s22
	s_nop 0
	global_load_lds_dwordx4 v130, s[28:29]
	s_mov_b32 m0, s23
	s_nop 0
	global_load_lds_dwordx4 v134, s[28:29]
	s_waitcnt vmcnt(8)
	s_waitcnt lgkmcnt(0)
	s_barrier
	s_waitcnt lgkmcnt(0)
	v_mfma_f32_16x16x32_bf16 v[60:63], v[146:149], v[184:187], v[60:63]
	v_mfma_f32_16x16x32_bf16 v[52:55], v[154:157], v[184:187], v[52:55]
	v_mfma_f32_16x16x32_bf16 v[36:39], v[154:157], v[192:195], v[36:39]
	v_mfma_f32_16x16x32_bf16 v[44:47], v[146:149], v[192:195], v[44:47]
	v_mfma_f32_16x16x32_bf16 v[28:31], v[146:149], v[200:203], v[28:31]
	v_mfma_f32_16x16x32_bf16 v[20:23], v[154:157], v[200:203], v[20:23]
	v_mfma_f32_16x16x32_bf16 v[4:7], v[154:157], v[208:211], v[4:7]
	v_mfma_f32_16x16x32_bf16 v[12:15], v[146:149], v[208:211], v[12:15]
	v_mfma_f32_16x16x32_bf16 v[60:63], v[150:153], v[188:191], v[60:63]
	v_mfma_f32_16x16x32_bf16 v[52:55], v[162:165], v[188:191], v[52:55]
	v_mfma_f32_16x16x32_bf16 v[36:39], v[162:165], v[196:199], v[36:39]
	v_mfma_f32_16x16x32_bf16 v[44:47], v[150:153], v[196:199], v[44:47]
	v_mfma_f32_16x16x32_bf16 v[28:31], v[150:153], v[204:207], v[28:31]
	v_mfma_f32_16x16x32_bf16 v[20:23], v[162:165], v[204:207], v[20:23]
	v_mfma_f32_16x16x32_bf16 v[4:7], v[162:165], v[212:215], v[4:7]
	v_mfma_f32_16x16x32_bf16 v[12:15], v[150:153], v[212:215], v[12:15]
	v_mfma_f32_16x16x32_bf16 v[56:59], v[166:169], v[184:187], v[56:59]
	v_mfma_f32_16x16x32_bf16 v[48:51], v[174:177], v[184:187], v[48:51]
	v_mfma_f32_16x16x32_bf16 v[32:35], v[174:177], v[192:195], v[32:35]
	v_mfma_f32_16x16x32_bf16 v[40:43], v[166:169], v[192:195], v[40:43]
	v_mfma_f32_16x16x32_bf16 v[24:27], v[166:169], v[200:203], v[24:27]
	v_mfma_f32_16x16x32_bf16 v[16:19], v[174:177], v[200:203], v[16:19]
	v_mfma_f32_16x16x32_bf16 v[0:3], v[174:177], v[208:211], v[0:3]
	v_mfma_f32_16x16x32_bf16 v[8:11], v[166:169], v[208:211], v[8:11]
	v_mfma_f32_16x16x32_bf16 v[56:59], v[170:173], v[188:191], v[56:59]
	v_mfma_f32_16x16x32_bf16 v[48:51], v[180:183], v[188:191], v[48:51]
	v_mfma_f32_16x16x32_bf16 v[32:35], v[180:183], v[196:199], v[32:35]
	v_mfma_f32_16x16x32_bf16 v[40:43], v[170:173], v[196:199], v[40:43]
	v_mfma_f32_16x16x32_bf16 v[24:27], v[170:173], v[204:207], v[24:27]
	v_mfma_f32_16x16x32_bf16 v[16:19], v[180:183], v[204:207], v[16:19]
	v_mfma_f32_16x16x32_bf16 v[0:3], v[180:183], v[212:215], v[0:3]
	v_mfma_f32_16x16x32_bf16 v[8:11], v[170:173], v[212:215], v[8:11]
	s_barrier
	ds_read_b128 v[146:149], v144
	ds_read_b128 v[150:153], v144 offset:1024
	ds_read_b128 v[154:157], v144 offset:2048
	ds_read_b128 v[162:165], v144 offset:3072
	ds_read_b128 v[166:169], v145
	ds_read_b128 v[170:173], v145 offset:1024
	ds_read_b128 v[174:177], v145 offset:2048
	ds_read_b128 v[180:183], v145 offset:3072
	s_add_u32 s8, s28, 0x4000
	s_addc_u32 s9, s29, 0
	s_mov_b32 m0, s39
	ds_read_b128 v[184:187], v161 offset:32768
	ds_read_b128 v[188:191], v161 offset:33792
	ds_read_b128 v[192:195], v161 offset:34816
	ds_read_b128 v[196:199], v161 offset:35840
	ds_read_b128 v[200:203], v161 offset:36864
	ds_read_b128 v[204:207], v161 offset:37888
	ds_read_b128 v[208:211], v161 offset:38912
	ds_read_b128 v[212:215], v161 offset:39936
	global_load_lds_dwordx4 v130, s[8:9]
	s_mov_b32 m0, s52
	s_nop 0
	global_load_lds_dwordx4 v134, s[8:9]
	s_waitcnt vmcnt(8)
	s_waitcnt lgkmcnt(0)
	s_barrier
; #define PG8_BAR __builtin_amdgcn_s_barrier()
; template <class Epi, class Sched, bool ALIGN_EPI = false, bool SP2 = false>
; __device__ __forceinline__ void gemm_phase(PG8_LAS unsigned char* lds, const Gemm g, const Sched& S, const Epi& E) {
;     ...
;         if constexpr (Epi::PEEL) {
;             const char* a1 = cA + kstepA; const char* a2 = cA + 2 * kstepA; const char* b2 = cB + 2 * kstepB; const char* a3 = a2 + kstepA; const char* b3 = b2 + kstepB;
;             PG8_ITER(8);
;         }
;         for (int t = (Epi::PEEL ? 2 : 0); t < nt; t += 2) {
;             const bool last = (t == nt - 2);
;             const char* a1 = cA + (size_t)(t + 1) * kstepA;
;             const char* a2 = last ? nA : cA + (size_t)(t + 2) * kstepA; const char* b2 = last ? nB : cB + (size_t)(t + 2) * kstepB;
;             const char* a3 = a2 + kstepA; const char* b3 = b2 + kstepB;
;             PG8_ITER(8);
;         }
;     ...
;         if constexpr (ALIGN_EPI) { if (wr == 0) PG8_BAR; }
	s_waitcnt lgkmcnt(0)
	v_mfma_f32_16x16x32_bf16 v[126:129], v[146:149], v[184:187], v[126:129]
	v_mfma_f32_16x16x32_bf16 v[118:121], v[154:157], v[184:187], v[118:121]
	v_mfma_f32_16x16x32_bf16 v[102:105], v[154:157], v[192:195], v[102:105]
	v_mfma_f32_16x16x32_bf16 v[110:113], v[146:149], v[192:195], v[110:113]
	v_mfma_f32_16x16x32_bf16 v[92:95], v[146:149], v[200:203], v[92:95]
	v_mfma_f32_16x16x32_bf16 v[84:87], v[154:157], v[200:203], v[84:87]
	v_mfma_f32_16x16x32_bf16 v[68:71], v[154:157], v[208:211], v[68:71]
	v_mfma_f32_16x16x32_bf16 v[76:79], v[146:149], v[208:211], v[76:79]
	v_mfma_f32_16x16x32_bf16 v[126:129], v[150:153], v[188:191], v[126:129]
	v_mfma_f32_16x16x32_bf16 v[118:121], v[162:165], v[188:191], v[118:121]
	v_mfma_f32_16x16x32_bf16 v[102:105], v[162:165], v[196:199], v[102:105]
	v_mfma_f32_16x16x32_bf16 v[110:113], v[150:153], v[196:199], v[110:113]
	v_mfma_f32_16x16x32_bf16 v[92:95], v[150:153], v[204:207], v[92:95]
	v_mfma_f32_16x16x32_bf16 v[84:87], v[162:165], v[204:207], v[84:87]
	v_mfma_f32_16x16x32_bf16 v[68:71], v[162:165], v[212:215], v[68:71]
	v_mfma_f32_16x16x32_bf16 v[76:79], v[150:153], v[212:215], v[76:79]
	v_mfma_f32_16x16x32_bf16 v[122:125], v[166:169], v[184:187], v[122:125]
	v_mfma_f32_16x16x32_bf16 v[114:117], v[174:177], v[184:187], v[114:117]
	v_mfma_f32_16x16x32_bf16 v[98:101], v[174:177], v[192:195], v[98:101]
	v_mfma_f32_16x16x32_bf16 v[106:109], v[166:169], v[192:195], v[106:109]
	v_mfma_f32_16x16x32_bf16 v[88:91], v[166:169], v[200:203], v[88:91]
	v_mfma_f32_16x16x32_bf16 v[80:83], v[174:177], v[200:203], v[80:83]
	v_mfma_f32_16x16x32_bf16 v[64:67], v[174:177], v[208:211], v[64:67]
	v_mfma_f32_16x16x32_bf16 v[72:75], v[166:169], v[208:211], v[72:75]
	v_mfma_f32_16x16x32_bf16 v[122:125], v[170:173], v[188:191], v[122:125]
	v_mfma_f32_16x16x32_bf16 v[114:117], v[180:183], v[188:191], v[114:117]
	v_mfma_f32_16x16x32_bf16 v[98:101], v[180:183], v[196:199], v[98:101]
	v_mfma_f32_16x16x32_bf16 v[106:109], v[170:173], v[196:199], v[106:109]
	v_mfma_f32_16x16x32_bf16 v[88:91], v[170:173], v[204:207], v[88:91]
	v_mfma_f32_16x16x32_bf16 v[80:83], v[180:183], v[204:207], v[80:83]
	v_mfma_f32_16x16x32_bf16 v[64:67], v[180:183], v[212:215], v[64:67]
	v_mfma_f32_16x16x32_bf16 v[72:75], v[170:173], v[212:215], v[72:75]
	s_barrier
	s_mov_b32 m0, s30
	s_add_u32 s100, s42, 0x80
	s_addc_u32 s101, s43, 0
	s_add_u32 s8, s42, 0x40080
	ds_read_b128 v[184:187], v161 offset:49152
	ds_read_b128 v[188:191], v161 offset:50176
	ds_read_b128 v[192:195], v161 offset:51200
	ds_read_b128 v[196:199], v161 offset:52224
	ds_read_b128 v[200:203], v161 offset:53248
	ds_read_b128 v[204:207], v161 offset:54272
	ds_read_b128 v[208:211], v161 offset:55296
	ds_read_b128 v[212:215], v161 offset:56320
	global_load_lds_dwordx4 v132, s[100:101]
	s_mov_b32 m0, s31
	s_addc_u32 s9, s43, 0
	global_load_lds_dwordx4 v136, s[100:101]
	s_mov_b32 m0, s57
	s_nop 0
	global_load_lds_dwordx4 v132, s[8:9]
	s_mov_b32 m0, s96
	s_nop 0
	global_load_lds_dwordx4 v136, s[8:9]
	s_mov_b32 m0, s11
	s_nop 0
	global_load_lds_dwordx4 v130, s[24:25]
	s_mov_b32 m0, s19
	s_nop 0
	global_load_lds_dwordx4 v134, s[24:25]
	s_waitcnt vmcnt(8)
	s_waitcnt lgkmcnt(0)
	s_barrier
	s_waitcnt lgkmcnt(0)
	v_mfma_f32_16x16x32_bf16 v[60:63], v[146:149], v[184:187], v[60:63]
	v_mfma_f32_16x16x32_bf16 v[52:55], v[154:157], v[184:187], v[52:55]
	v_mfma_f32_16x16x32_bf16 v[36:39], v[154:157], v[192:195], v[36:39]
	v_mfma_f32_16x16x32_bf16 v[44:47], v[146:149], v[192:195], v[44:47]
	v_mfma_f32_16x16x32_bf16 v[28:31], v[146:149], v[200:203], v[28:31]
	v_mfma_f32_16x16x32_bf16 v[20:23], v[154:157], v[200:203], v[20:23]
	v_mfma_f32_16x16x32_bf16 v[4:7], v[154:157], v[208:211], v[4:7]
	v_mfma_f32_16x16x32_bf16 v[12:15], v[146:149], v[208:211], v[12:15]
	v_mfma_f32_16x16x32_bf16 v[60:63], v[150:153], v[188:191], v[60:63]
	v_mfma_f32_16x16x32_bf16 v[52:55], v[162:165], v[188:191], v[52:55]
	v_mfma_f32_16x16x32_bf16 v[36:39], v[162:165], v[196:199], v[36:39]
	v_mfma_f32_16x16x32_bf16 v[44:47], v[150:153], v[196:199], v[44:47]
	v_mfma_f32_16x16x32_bf16 v[28:31], v[150:153], v[204:207], v[28:31]
	v_mfma_f32_16x16x32_bf16 v[20:23], v[162:165], v[204:207], v[20:23]
	v_mfma_f32_16x16x32_bf16 v[4:7], v[162:165], v[212:215], v[4:7]
	v_mfma_f32_16x16x32_bf16 v[12:15], v[150:153], v[212:215], v[12:15]
	v_mfma_f32_16x16x32_bf16 v[56:59], v[166:169], v[184:187], v[56:59]
	v_mfma_f32_16x16x32_bf16 v[48:51], v[174:177], v[184:187], v[48:51]
	v_mfma_f32_16x16x32_bf16 v[32:35], v[174:177], v[192:195], v[32:35]
	v_mfma_f32_16x16x32_bf16 v[40:43], v[166:169], v[192:195], v[40:43]
	v_mfma_f32_16x16x32_bf16 v[24:27], v[166:169], v[200:203], v[24:27]
	v_mfma_f32_16x16x32_bf16 v[16:19], v[174:177], v[200:203], v[16:19]
	v_mfma_f32_16x16x32_bf16 v[0:3], v[174:177], v[208:211], v[0:3]
	v_mfma_f32_16x16x32_bf16 v[8:11], v[166:169], v[208:211], v[8:11]
	v_mfma_f32_16x16x32_bf16 v[56:59], v[170:173], v[188:191], v[56:59]
	v_mfma_f32_16x16x32_bf16 v[48:51], v[180:183], v[188:191], v[48:51]
	v_mfma_f32_16x16x32_bf16 v[32:35], v[180:183], v[196:199], v[32:35]
	v_mfma_f32_16x16x32_bf16 v[40:43], v[170:173], v[196:199], v[40:43]
	v_mfma_f32_16x16x32_bf16 v[24:27], v[170:173], v[204:207], v[24:27]
	v_mfma_f32_16x16x32_bf16 v[16:19], v[180:183], v[204:207], v[16:19]
	v_mfma_f32_16x16x32_bf16 v[0:3], v[180:183], v[212:215], v[0:3]
	v_mfma_f32_16x16x32_bf16 v[8:11], v[170:173], v[212:215], v[8:11]
	s_barrier
	s_add_i32 s18, s18, 2
	s_add_u32 s3, s3, 0x100
	s_addc_u32 s2, s2, 0
	s_add_u32 s0, s0, 0x800000
	s_addc_u32 s1, s1, 0
	s_cmp_gt_u32 s18, 13
	s_cbranch_scc0 .LBB0_161
	v_readlane_b32 s0, v255, 45
	v_readlane_b32 s1, v255, 46
	s_and_b64 vcc, exec, s[0:1]
	s_cbranch_vccz .LBB0_164
	s_barrier

; template <class Epi, class Sched, bool ALIGN_EPI = false, bool SP2 = false>
; __device__ __forceinline__ void gemm_phase(PG8_LAS unsigned char* lds, const Gemm g, const Sched& S, const Epi& E) {
;     ...
;         if constexpr (Epi::PEEL) {
;             const char* a1 = cA + kstepA; const char* a2 = cA + 2 * kstepA; const char* b2 = cB + 2 * kstepB; const char* a3 = a2 + kstepA; const char* b3 = b2 + kstepB;
;             PG8_ITER(8);
;         }
.LBB0_249:
	s_ashr_i32 s49, s48, 31
	s_lshl_b64 s[2:3], s[48:49], 15
	v_readlane_b32 s11, v255, 15
	s_add_u32 s50, s11, s2
	v_readlane_b32 s2, v255, 16
	s_addc_u32 s51, s2, s3
	s_ashr_i32 s47, s46, 31
	s_lshl_b64 s[2:3], s[46:47], 19
	s_add_u32 s52, s38, s2
	s_addc_u32 s53, s19, s3
	s_add_u32 s28, s42, 0x800000
	s_addc_u32 s29, s43, 0
	s_add_u32 s44, s42, 0xc00000
	s_addc_u32 s45, s43, 0
	s_add_i32 s99, 0, 0x10000
	s_and_b64 s[2:3], s[40:41], exec
	s_cselect_b32 s27, s51, s43
	s_cselect_b32 s47, s50, s42
	s_add_i32 vcc_hi, 0, 0x14000
	v_add_u32_e32 v130, s99, v97
	v_add_u32_e32 v131, vcc_hi, v97
	ds_read_b128 v[0:3], v130
	ds_read_b128 v[4:7], v130 offset:1024
	ds_read_b128 v[8:11], v130 offset:2048
	ds_read_b128 v[12:15], v130 offset:3072
	ds_read_b128 v[16:19], v131
	s_waitcnt lgkmcnt(0)
	ds_read_b128 v[20:23], v131 offset:1024
	ds_read_b128 v[24:27], v131 offset:2048
	ds_read_b128 v[28:31], v131 offset:3072
	s_and_b64 s[2:3], s[40:41], exec
	s_cselect_b32 s49, s53, s25
	s_cselect_b32 s54, s52, s24
	s_add_u32 s2, s42, 0x404000
	s_addc_u32 s3, s43, 0
	s_add_i32 s55, s22, 0xc000
	s_mov_b32 m0, s55
	s_add_i32 s98, s22, 0xe000
	ds_read_b128 v[32:35], v151
	ds_read_b128 v[36:39], v151 offset:1024
	ds_read_b128 v[40:43], v151 offset:2048
	ds_read_b128 v[44:47], v151 offset:3072
	ds_read_b128 v[48:51], v151 offset:4096
	ds_read_b128 v[52:55], v151 offset:5120
	ds_read_b128 v[56:59], v151 offset:6144
	ds_read_b128 v[60:63], v151 offset:7168
	global_load_lds_dwordx4 v134, s[2:3]
	s_mov_b32 m0, s98
	s_nop 0
	global_load_lds_dwordx4 v138, s[2:3]
	s_waitcnt vmcnt(8)
	s_waitcnt lgkmcnt(0)
	s_barrier
	s_waitcnt lgkmcnt(0)
	v_mfma_f32_16x16x32_bf16 v[84:87], v[8:11], v[48:51], 0
	v_mfma_f32_16x16x32_bf16 v[88:91], v[12:15], v[52:55], v[84:87]
	v_mfma_f32_16x16x32_bf16 v[84:87], v[0:3], v[56:59], 0
	v_mfma_f32_16x16x32_bf16 v[64:67], v[0:3], v[32:35], 0
	v_mfma_f32_16x16x32_bf16 v[68:71], v[8:11], v[32:35], 0
	v_mfma_f32_16x16x32_bf16 v[72:75], v[0:3], v[40:43], 0
	v_mfma_f32_16x16x32_bf16 v[76:79], v[8:11], v[40:43], 0
	v_mfma_f32_16x16x32_bf16 v[80:83], v[0:3], v[48:51], 0
	v_mfma_f32_16x16x32_bf16 v[92:95], v[4:7], v[60:63], v[84:87]
	v_mfma_f32_16x16x32_bf16 v[84:87], v[8:11], v[56:59], 0
	v_mfma_f32_16x16x32_bf16 v[64:67], v[4:7], v[36:39], v[64:67]
	v_mfma_f32_16x16x32_bf16 v[68:71], v[12:15], v[36:39], v[68:71]
	v_mfma_f32_16x16x32_bf16 v[72:75], v[4:7], v[44:47], v[72:75]
	v_mfma_f32_16x16x32_bf16 v[76:79], v[12:15], v[44:47], v[76:79]
	v_mfma_f32_16x16x32_bf16 v[80:83], v[4:7], v[52:55], v[80:83]
	v_mfma_f32_16x16x32_bf16 v[106:109], v[12:15], v[60:63], v[84:87]
	v_mfma_f32_16x16x32_bf16 v[84:87], v[16:19], v[32:35], 0
	v_mfma_f32_16x16x32_bf16 v[32:35], v[24:27], v[32:35], 0
	v_mfma_f32_16x16x32_bf16 v[110:113], v[20:23], v[36:39], v[84:87]
	v_mfma_f32_16x16x32_bf16 v[32:35], v[28:31], v[36:39], v[32:35]
	v_mfma_f32_16x16x32_bf16 v[36:39], v[16:19], v[40:43], 0
	v_mfma_f32_16x16x32_bf16 v[40:43], v[24:27], v[40:43], 0
	v_mfma_f32_16x16x32_bf16 v[36:39], v[20:23], v[44:47], v[36:39]
	v_mfma_f32_16x16x32_bf16 v[40:43], v[28:31], v[44:47], v[40:43]
	v_mfma_f32_16x16x32_bf16 v[44:47], v[16:19], v[48:51], 0
	v_mfma_f32_16x16x32_bf16 v[48:51], v[24:27], v[48:51], 0
	v_mfma_f32_16x16x32_bf16 v[44:47], v[20:23], v[52:55], v[44:47]
	v_mfma_f32_16x16x32_bf16 v[48:51], v[28:31], v[52:55], v[48:51]
	v_mfma_f32_16x16x32_bf16 v[52:55], v[16:19], v[56:59], 0
	v_mfma_f32_16x16x32_bf16 v[56:59], v[24:27], v[56:59], 0
	v_mfma_f32_16x16x32_bf16 v[52:55], v[20:23], v[60:63], v[52:55]
	v_mfma_f32_16x16x32_bf16 v[56:59], v[28:31], v[60:63], v[56:59]
	s_barrier
	v_lshl_add_u64 v[176:177], s[24:25], 0, v[136:137]
	s_mov_b64 s[2:3], 0x100
	s_add_i32 s99, s99, s10
	v_lshl_add_u64 v[132:133], v[176:177], 0, s[2:3]
	s_mov_b32 m0, s99
	v_lshl_add_u64 v[178:179], s[24:25], 0, v[140:141]
	s_add_i32 vcc_lo, s99, 0x2000
	ds_read_b128 v[60:63], v151 offset:16384
	ds_read_b128 v[84:87], v151 offset:17408
	ds_read_b128 v[98:101], v151 offset:18432
	ds_read_b128 v[102:105], v151 offset:19456
	ds_read_b128 v[114:117], v151 offset:20480
	ds_read_b128 v[118:121], v151 offset:21504
	ds_read_b128 v[122:125], v151 offset:22528
	ds_read_b128 v[126:129], v151 offset:23552
	global_load_lds_dwordx4 v[132:133], off
	v_lshl_add_u64 v[132:133], v[178:179], 0, s[2:3]
	s_add_u32 s2, s24, 0x40100
	s_mov_b32 m0, vcc_lo
	s_addc_u32 s3, s25, 0
	s_add_i32 vcc_hi, vcc_hi, s10
	global_load_lds_dwordx4 v[132:133], off
	s_mov_b32 m0, vcc_hi
	s_add_i32 s30, vcc_hi, 0x2000
	global_load_lds_dwordx4 v136, s[2:3]
	s_mov_b32 m0, s30
	s_mov_b64 s[34:35], 0x100
	global_load_lds_dwordx4 v140, s[2:3]
	s_mov_b32 m0, s22
	s_nop 0
	global_load_lds_dwordx4 v134, s[28:29]
	s_mov_b32 m0, s23
	s_nop 0
	global_load_lds_dwordx4 v138, s[28:29]
	s_waitcnt vmcnt(8)
	s_waitcnt lgkmcnt(0)
	s_barrier
; template <class Epi, class Sched, bool ALIGN_EPI = false, bool SP2 = false>
; __device__ __forceinline__ void gemm_phase(PG8_LAS unsigned char* lds, const Gemm g, const Sched& S, const Epi& E) {
;     ...
;         if constexpr (Epi::PEEL) {
;             const char* a1 = cA + kstepA; const char* a2 = cA + 2 * kstepA; const char* b2 = cB + 2 * kstepB; const char* a3 = a2 + kstepA; const char* b3 = b2 + kstepB;
;             PG8_ITER(8);
;         }
	s_waitcnt lgkmcnt(0)
	v_mfma_f32_16x16x32_bf16 v[146:149], v[0:3], v[60:63], 0
	v_mfma_f32_16x16x32_bf16 v[156:159], v[0:3], v[98:101], 0
	v_mfma_f32_16x16x32_bf16 v[164:167], v[0:3], v[114:117], 0
	v_mfma_f32_16x16x32_bf16 v[0:3], v[0:3], v[122:125], 0
	v_mfma_f32_16x16x32_bf16 v[146:149], v[4:7], v[84:87], v[146:149]
	v_mfma_f32_16x16x32_bf16 v[156:159], v[4:7], v[102:105], v[156:159]
	v_mfma_f32_16x16x32_bf16 v[164:167], v[4:7], v[118:121], v[164:167]
	v_mfma_f32_16x16x32_bf16 v[0:3], v[4:7], v[126:129], v[0:3]
	v_mfma_f32_16x16x32_bf16 v[4:7], v[8:11], v[122:125], 0
	v_mfma_f32_16x16x32_bf16 v[152:155], v[8:11], v[60:63], 0
	v_mfma_f32_16x16x32_bf16 v[160:163], v[8:11], v[98:101], 0
	v_mfma_f32_16x16x32_bf16 v[168:171], v[8:11], v[114:117], 0
	v_mfma_f32_16x16x32_bf16 v[8:11], v[12:15], v[126:129], v[4:7]
	v_mfma_f32_16x16x32_bf16 v[152:155], v[12:15], v[84:87], v[152:155]
	v_mfma_f32_16x16x32_bf16 v[160:163], v[12:15], v[102:105], v[160:163]
	v_mfma_f32_16x16x32_bf16 v[168:171], v[12:15], v[118:121], v[168:171]
	v_mfma_f32_16x16x32_bf16 v[4:7], v[16:19], v[60:63], 0
	v_mfma_f32_16x16x32_bf16 v[12:15], v[20:23], v[84:87], v[4:7]
	v_mfma_f32_16x16x32_bf16 v[4:7], v[24:27], v[60:63], 0
	v_mfma_f32_16x16x32_bf16 v[172:175], v[28:31], v[84:87], v[4:7]
	v_mfma_f32_16x16x32_bf16 v[4:7], v[16:19], v[98:101], 0
	v_mfma_f32_16x16x32_bf16 v[180:183], v[20:23], v[102:105], v[4:7]
	v_mfma_f32_16x16x32_bf16 v[4:7], v[24:27], v[98:101], 0
	v_mfma_f32_16x16x32_bf16 v[184:187], v[28:31], v[102:105], v[4:7]
	v_mfma_f32_16x16x32_bf16 v[4:7], v[16:19], v[114:117], 0
	v_mfma_f32_16x16x32_bf16 v[188:191], v[20:23], v[118:121], v[4:7]
	v_mfma_f32_16x16x32_bf16 v[4:7], v[24:27], v[114:117], 0
	v_mfma_f32_16x16x32_bf16 v[192:195], v[28:31], v[118:121], v[4:7]
	v_mfma_f32_16x16x32_bf16 v[4:7], v[16:19], v[122:125], 0
	v_mfma_f32_16x16x32_bf16 v[196:199], v[20:23], v[126:129], v[4:7]
	v_mfma_f32_16x16x32_bf16 v[4:7], v[24:27], v[122:125], 0
	v_mfma_f32_16x16x32_bf16 v[200:203], v[28:31], v[126:129], v[4:7]
	s_barrier
	s_add_i32 s31, 0, 0x18000
	s_add_i32 s13, 0, 0x1c000
	v_add_u32_e32 v132, s31, v97
	v_add_u32_e32 v133, s13, v97
	s_nop 0
	ds_read_b128 v[4:7], v132
	ds_read_b128 v[24:27], v132 offset:1024
	ds_read_b128 v[28:31], v132 offset:2048
	ds_read_b128 v[60:63], v132 offset:3072
	ds_read_b128 v[204:207], v133
	ds_read_b128 v[208:211], v133 offset:1024
	ds_read_b128 v[212:215], v133 offset:2048
	ds_read_b128 v[216:219], v133 offset:3072
	s_add_u32 s2, s42, 0x804000
	s_addc_u32 s3, s43, 0
	s_mov_b32 m0, s39
	ds_read_b128 v[16:19], v151 offset:32768
	ds_read_b128 v[20:23], v151 offset:33792
	ds_read_b128 v[220:223], v151 offset:34816
	ds_read_b128 v[224:227], v151 offset:35840
	ds_read_b128 v[228:231], v151 offset:36864
	ds_read_b128 v[234:237], v151 offset:37888
	ds_read_b128 v[238:241], v151 offset:38912
	ds_read_b128 v[242:245], v151 offset:39936
	global_load_lds_dwordx4 v134, s[2:3]
	s_mov_b32 m0, s56
	s_nop 0
	global_load_lds_dwordx4 v138, s[2:3]
	s_waitcnt vmcnt(8)
	s_waitcnt lgkmcnt(0)
	s_barrier
	s_waitcnt lgkmcnt(0)
	v_mfma_f32_16x16x32_bf16 v[64:67], v[4:7], v[16:19], v[64:67]
	v_mfma_f32_16x16x32_bf16 v[118:121], v[24:27], v[20:23], v[64:67]
	v_mfma_f32_16x16x32_bf16 v[64:67], v[28:31], v[16:19], v[68:71]
	v_mfma_f32_16x16x32_bf16 v[114:117], v[60:63], v[20:23], v[64:67]
	v_mfma_f32_16x16x32_bf16 v[64:67], v[4:7], v[220:223], v[72:75]
	v_mfma_f32_16x16x32_bf16 v[102:105], v[24:27], v[224:227], v[64:67]
	v_mfma_f32_16x16x32_bf16 v[64:67], v[28:31], v[220:223], v[76:79]
	v_mfma_f32_16x16x32_bf16 v[98:101], v[60:63], v[224:227], v[64:67]
	v_mfma_f32_16x16x32_bf16 v[64:67], v[4:7], v[228:231], v[80:83]
	v_mfma_f32_16x16x32_bf16 v[84:87], v[24:27], v[234:237], v[64:67]
	v_mfma_f32_16x16x32_bf16 v[64:67], v[28:31], v[228:231], v[88:91]
	v_mfma_f32_16x16x32_bf16 v[80:83], v[60:63], v[234:237], v[64:67]
	v_mfma_f32_16x16x32_bf16 v[64:67], v[4:7], v[238:241], v[92:95]
	v_mfma_f32_16x16x32_bf16 v[68:71], v[24:27], v[242:245], v[64:67]
	v_mfma_f32_16x16x32_bf16 v[64:67], v[28:31], v[238:241], v[106:109]
	v_mfma_f32_16x16x32_bf16 v[64:67], v[60:63], v[242:245], v[64:67]
	v_mfma_f32_16x16x32_bf16 v[72:75], v[204:207], v[16:19], v[110:113]
	v_mfma_f32_16x16x32_bf16 v[16:19], v[212:215], v[16:19], v[32:35]
	v_mfma_f32_16x16x32_bf16 v[122:125], v[216:219], v[20:23], v[16:19]
	v_mfma_f32_16x16x32_bf16 v[16:19], v[204:207], v[220:223], v[36:39]
	v_mfma_f32_16x16x32_bf16 v[110:113], v[208:211], v[224:227], v[16:19]
	v_mfma_f32_16x16x32_bf16 v[16:19], v[212:215], v[220:223], v[40:43]
	v_mfma_f32_16x16x32_bf16 v[106:109], v[216:219], v[224:227], v[16:19]
	v_mfma_f32_16x16x32_bf16 v[16:19], v[204:207], v[228:231], v[44:47]
	v_mfma_f32_16x16x32_bf16 v[92:95], v[208:211], v[234:237], v[16:19]
	v_mfma_f32_16x16x32_bf16 v[16:19], v[212:215], v[228:231], v[48:51]
	v_mfma_f32_16x16x32_bf16 v[88:91], v[216:219], v[234:237], v[16:19]
	v_mfma_f32_16x16x32_bf16 v[16:19], v[204:207], v[238:241], v[52:55]
	v_mfma_f32_16x16x32_bf16 v[76:79], v[208:211], v[242:245], v[16:19]
	v_mfma_f32_16x16x32_bf16 v[16:19], v[212:215], v[238:241], v[56:59]
	v_mfma_f32_16x16x32_bf16 v[126:129], v[208:211], v[20:23], v[72:75]
	v_mfma_f32_16x16x32_bf16 v[72:75], v[216:219], v[242:245], v[16:19]
	s_barrier
; template <class Epi, class Sched, bool ALIGN_EPI = false, bool SP2 = false>
; __device__ __forceinline__ void gemm_phase(PG8_LAS unsigned char* lds, const Gemm g, const Sched& S, const Epi& E) {
;     ...
;         if constexpr (Epi::PEEL) {
;             const char* a1 = cA + kstepA; const char* a2 = cA + 2 * kstepA; const char* b2 = cB + 2 * kstepB; const char* a3 = a2 + kstepA; const char* b3 = b2 + kstepB;
;             PG8_ITER(8);
;         }
;         for (int t = (Epi::PEEL ? 2 : 0); t < nt; t += 2) {
;             const bool last = (t == nt - 2);
;             const char* a1 = cA + (size_t)(t + 1) * kstepA;
;             const char* a2 = last ? nA : cA + (size_t)(t + 2) * kstepA; const char* b2 = last ? nB : cB + (size_t)(t + 2) * kstepB;
;             const char* a3 = a2 + kstepA; const char* b3 = b2 + kstepB;
;             PG8_ITER(8);
;         }
	s_mov_b64 s[2:3], 0x180
	s_add_i32 s31, s31, s10
	s_nop 1
	v_lshl_add_u64 v[16:17], v[176:177], 0, s[2:3]
	s_mov_b32 m0, s31
	s_add_i32 s12, s31, 0x2000
	ds_read_b128 v[40:43], v151 offset:49152
	ds_read_b128 v[44:47], v151 offset:50176
	ds_read_b128 v[220:223], v151 offset:51200
	ds_read_b128 v[224:227], v151 offset:52224
	ds_read_b128 v[228:231], v151 offset:53248
	ds_read_b128 v[234:237], v151 offset:54272
	ds_read_b128 v[238:241], v151 offset:55296
	ds_read_b128 v[242:245], v151 offset:56320
	global_load_lds_dwordx4 v[16:17], off
	v_lshl_add_u64 v[16:17], v[178:179], 0, s[2:3]
	s_add_u32 s2, s24, 0x40180
	s_mov_b32 m0, s12
	s_addc_u32 s3, s25, 0
	s_add_i32 s13, s13, s10
	global_load_lds_dwordx4 v[16:17], off
	s_mov_b32 m0, s13
	s_add_i32 s11, s13, 0x2000
	global_load_lds_dwordx4 v136, s[2:3]
	s_mov_b32 m0, s11
	s_nop 0
	global_load_lds_dwordx4 v140, s[2:3]
	s_mov_b32 m0, s59
	s_nop 0
	global_load_lds_dwordx4 v134, s[44:45]
	s_mov_b32 m0, s96
	s_nop 0
	global_load_lds_dwordx4 v138, s[44:45]
	s_waitcnt vmcnt(8)
	s_waitcnt lgkmcnt(0)
	s_barrier
	s_waitcnt lgkmcnt(0)
	v_mfma_f32_16x16x32_bf16 v[16:19], v[4:7], v[40:43], v[146:149]
	v_mfma_f32_16x16x32_bf16 v[52:55], v[24:27], v[44:47], v[16:19]
	v_mfma_f32_16x16x32_bf16 v[16:19], v[28:31], v[40:43], v[152:155]
	v_mfma_f32_16x16x32_bf16 v[48:51], v[60:63], v[44:47], v[16:19]
	v_mfma_f32_16x16x32_bf16 v[16:19], v[4:7], v[220:223], v[156:159]
	v_mfma_f32_16x16x32_bf16 v[36:39], v[24:27], v[224:227], v[16:19]
	v_mfma_f32_16x16x32_bf16 v[16:19], v[28:31], v[220:223], v[160:163]
	v_mfma_f32_16x16x32_bf16 v[32:35], v[60:63], v[224:227], v[16:19]
	v_mfma_f32_16x16x32_bf16 v[16:19], v[4:7], v[228:231], v[164:167]
	v_mfma_f32_16x16x32_bf16 v[0:3], v[4:7], v[238:241], v[0:3]
	v_mfma_f32_16x16x32_bf16 v[20:23], v[24:27], v[234:237], v[16:19]
	v_mfma_f32_16x16x32_bf16 v[16:19], v[28:31], v[228:231], v[168:171]
	v_mfma_f32_16x16x32_bf16 v[4:7], v[24:27], v[242:245], v[0:3]
	v_mfma_f32_16x16x32_bf16 v[0:3], v[28:31], v[238:241], v[8:11]
	v_mfma_f32_16x16x32_bf16 v[16:19], v[60:63], v[234:237], v[16:19]
	v_mfma_f32_16x16x32_bf16 v[0:3], v[60:63], v[242:245], v[0:3]
	v_mfma_f32_16x16x32_bf16 v[8:11], v[204:207], v[40:43], v[12:15]
	v_mfma_f32_16x16x32_bf16 v[60:63], v[208:211], v[44:47], v[8:11]
	v_mfma_f32_16x16x32_bf16 v[8:11], v[212:215], v[40:43], v[172:175]
	v_mfma_f32_16x16x32_bf16 v[56:59], v[216:219], v[44:47], v[8:11]
	v_mfma_f32_16x16x32_bf16 v[8:11], v[204:207], v[220:223], v[180:183]
	v_mfma_f32_16x16x32_bf16 v[44:47], v[208:211], v[224:227], v[8:11]
	v_mfma_f32_16x16x32_bf16 v[8:11], v[212:215], v[220:223], v[184:187]
	v_mfma_f32_16x16x32_bf16 v[40:43], v[216:219], v[224:227], v[8:11]
	v_mfma_f32_16x16x32_bf16 v[8:11], v[204:207], v[228:231], v[188:191]
	v_mfma_f32_16x16x32_bf16 v[28:31], v[208:211], v[234:237], v[8:11]
	v_mfma_f32_16x16x32_bf16 v[8:11], v[212:215], v[228:231], v[192:195]
	v_mfma_f32_16x16x32_bf16 v[24:27], v[216:219], v[234:237], v[8:11]
	v_mfma_f32_16x16x32_bf16 v[8:11], v[204:207], v[238:241], v[196:199]
	v_mfma_f32_16x16x32_bf16 v[12:15], v[208:211], v[242:245], v[8:11]
	v_mfma_f32_16x16x32_bf16 v[8:11], v[212:215], v[238:241], v[200:203]
	v_mfma_f32_16x16x32_bf16 v[8:11], v[216:219], v[242:245], v[8:11]
	s_barrier
	s_add_u32 s3, s24, 0x200
	s_addc_u32 s2, s25, 0
	s_add_u32 s24, s42, 0xc04000
	s_addc_u32 s25, s43, 0
	s_mov_b32 s18, 0
.LBB0_250:
	ds_read_b128 v[146:149], v130
	ds_read_b128 v[152:155], v130 offset:1024
	ds_read_b128 v[156:159], v130 offset:2048
	ds_read_b128 v[160:163], v130 offset:3072
	ds_read_b128 v[164:167], v131
	ds_read_b128 v[168:171], v131 offset:1024
	ds_read_b128 v[172:175], v131 offset:2048
	ds_read_b128 v[180:183], v131 offset:3072
	s_add_u32 s16, s24, 0x3fc000
	s_addc_u32 s17, s25, 0
	s_cmp_eq_u32 s18, 12
	s_cselect_b32 s28, s47, s16
	s_cselect_b32 s29, s27, s17
	s_cselect_b32 s44, s54, s3
	s_cselect_b32 s45, s49, s2
	s_add_u32 s42, s28, 0x400000
	s_addc_u32 s43, s29, 0
	s_mov_b32 m0, s55
	ds_read_b128 v[184:187], v151
	ds_read_b128 v[188:191], v151 offset:1024
	ds_read_b128 v[192:195], v151 offset:2048
	ds_read_b128 v[196:199], v151 offset:3072
	ds_read_b128 v[200:203], v151 offset:4096
	ds_read_b128 v[204:207], v151 offset:5120
	ds_read_b128 v[208:211], v151 offset:6144
	ds_read_b128 v[212:215], v151 offset:7168
	global_load_lds_dwordx4 v144, s[24:25]
	s_mov_b32 m0, s98
	s_nop 0
	global_load_lds_dwordx4 v142, s[24:25]
	s_waitcnt vmcnt(8)
	s_waitcnt lgkmcnt(0)
	s_barrier
	s_waitcnt lgkmcnt(0)
	v_mfma_f32_16x16x32_bf16 v[118:121], v[146:149], v[184:187], v[118:121]
	v_mfma_f32_16x16x32_bf16 v[114:117], v[156:159], v[184:187], v[114:117]
	v_mfma_f32_16x16x32_bf16 v[98:101], v[156:159], v[192:195], v[98:101]
	v_mfma_f32_16x16x32_bf16 v[102:105], v[146:149], v[192:195], v[102:105]
	v_mfma_f32_16x16x32_bf16 v[84:87], v[146:149], v[200:203], v[84:87]
	v_mfma_f32_16x16x32_bf16 v[80:83], v[156:159], v[200:203], v[80:83]
	v_mfma_f32_16x16x32_bf16 v[64:67], v[156:159], v[208:211], v[64:67]
	v_mfma_f32_16x16x32_bf16 v[68:71], v[146:149], v[208:211], v[68:71]
	v_mfma_f32_16x16x32_bf16 v[118:121], v[152:155], v[188:191], v[118:121]
	v_mfma_f32_16x16x32_bf16 v[114:117], v[160:163], v[188:191], v[114:117]
	v_mfma_f32_16x16x32_bf16 v[98:101], v[160:163], v[196:199], v[98:101]
	v_mfma_f32_16x16x32_bf16 v[102:105], v[152:155], v[196:199], v[102:105]
	v_mfma_f32_16x16x32_bf16 v[84:87], v[152:155], v[204:207], v[84:87]
	v_mfma_f32_16x16x32_bf16 v[80:83], v[160:163], v[204:207], v[80:83]
	v_mfma_f32_16x16x32_bf16 v[64:67], v[160:163], v[212:215], v[64:67]
	v_mfma_f32_16x16x32_bf16 v[68:71], v[152:155], v[212:215], v[68:71]
	v_mfma_f32_16x16x32_bf16 v[126:129], v[164:167], v[184:187], v[126:129]
	v_mfma_f32_16x16x32_bf16 v[122:125], v[172:175], v[184:187], v[122:125]
	v_mfma_f32_16x16x32_bf16 v[106:109], v[172:175], v[192:195], v[106:109]
	v_mfma_f32_16x16x32_bf16 v[110:113], v[164:167], v[192:195], v[110:113]
	v_mfma_f32_16x16x32_bf16 v[92:95], v[164:167], v[200:203], v[92:95]
	v_mfma_f32_16x16x32_bf16 v[88:91], v[172:175], v[200:203], v[88:91]
	v_mfma_f32_16x16x32_bf16 v[72:75], v[172:175], v[208:211], v[72:75]
	v_mfma_f32_16x16x32_bf16 v[76:79], v[164:167], v[208:211], v[76:79]
	v_mfma_f32_16x16x32_bf16 v[126:129], v[168:171], v[188:191], v[126:129]
	v_mfma_f32_16x16x32_bf16 v[122:125], v[180:183], v[188:191], v[122:125]
	v_mfma_f32_16x16x32_bf16 v[106:109], v[180:183], v[196:199], v[106:109]
	v_mfma_f32_16x16x32_bf16 v[110:113], v[168:171], v[196:199], v[110:113]
	v_mfma_f32_16x16x32_bf16 v[92:95], v[168:171], v[204:207], v[92:95]
	v_mfma_f32_16x16x32_bf16 v[88:91], v[180:183], v[204:207], v[88:91]
	v_mfma_f32_16x16x32_bf16 v[72:75], v[180:183], v[212:215], v[72:75]
	v_mfma_f32_16x16x32_bf16 v[76:79], v[168:171], v[212:215], v[76:79]
	s_barrier
	s_mov_b32 m0, s99
	s_add_u32 s16, s44, 0x40000
	ds_read_b128 v[184:187], v151 offset:16384
	ds_read_b128 v[188:191], v151 offset:17408
	ds_read_b128 v[192:195], v151 offset:18432
	ds_read_b128 v[196:199], v151 offset:19456
	ds_read_b128 v[200:203], v151 offset:20480
	ds_read_b128 v[204:207], v151 offset:21504
	ds_read_b128 v[208:211], v151 offset:22528
	ds_read_b128 v[212:215], v151 offset:23552
	global_load_lds_dwordx4 v136, s[44:45]
	s_mov_b32 m0, vcc_lo
	s_addc_u32 s17, s45, 0
	global_load_lds_dwordx4 v140, s[44:45]
	s_mov_b32 m0, vcc_hi
	s_nop 0
	global_load_lds_dwordx4 v136, s[16:17]
	s_mov_b32 m0, s30
	s_nop 0
	global_load_lds_dwordx4 v140, s[16:17]
	s_mov_b32 m0, s22
	s_nop 0
	global_load_lds_dwordx4 v134, s[28:29]
	s_mov_b32 m0, s23
	s_nop 0
	global_load_lds_dwordx4 v138, s[28:29]
	s_waitcnt vmcnt(8)
	s_waitcnt lgkmcnt(0)
	s_barrier
	s_waitcnt lgkmcnt(0)
	v_mfma_f32_16x16x32_bf16 v[52:55], v[146:149], v[184:187], v[52:55]
	v_mfma_f32_16x16x32_bf16 v[48:51], v[156:159], v[184:187], v[48:51]
	v_mfma_f32_16x16x32_bf16 v[32:35], v[156:159], v[192:195], v[32:35]
	v_mfma_f32_16x16x32_bf16 v[36:39], v[146:149], v[192:195], v[36:39]
	v_mfma_f32_16x16x32_bf16 v[20:23], v[146:149], v[200:203], v[20:23]
	v_mfma_f32_16x16x32_bf16 v[16:19], v[156:159], v[200:203], v[16:19]
	v_mfma_f32_16x16x32_bf16 v[0:3], v[156:159], v[208:211], v[0:3]
	v_mfma_f32_16x16x32_bf16 v[4:7], v[146:149], v[208:211], v[4:7]
	v_mfma_f32_16x16x32_bf16 v[52:55], v[152:155], v[188:191], v[52:55]
	v_mfma_f32_16x16x32_bf16 v[48:51], v[160:163], v[188:191], v[48:51]
	v_mfma_f32_16x16x32_bf16 v[32:35], v[160:163], v[196:199], v[32:35]
	v_mfma_f32_16x16x32_bf16 v[36:39], v[152:155], v[196:199], v[36:39]
	v_mfma_f32_16x16x32_bf16 v[20:23], v[152:155], v[204:207], v[20:23]
	v_mfma_f32_16x16x32_bf16 v[16:19], v[160:163], v[204:207], v[16:19]
	v_mfma_f32_16x16x32_bf16 v[0:3], v[160:163], v[212:215], v[0:3]
	v_mfma_f32_16x16x32_bf16 v[4:7], v[152:155], v[212:215], v[4:7]
	v_mfma_f32_16x16x32_bf16 v[60:63], v[164:167], v[184:187], v[60:63]
	v_mfma_f32_16x16x32_bf16 v[56:59], v[172:175], v[184:187], v[56:59]
	v_mfma_f32_16x16x32_bf16 v[40:43], v[172:175], v[192:195], v[40:43]
	v_mfma_f32_16x16x32_bf16 v[44:47], v[164:167], v[192:195], v[44:47]
	v_mfma_f32_16x16x32_bf16 v[28:31], v[164:167], v[200:203], v[28:31]
	v_mfma_f32_16x16x32_bf16 v[24:27], v[172:175], v[200:203], v[24:27]
	v_mfma_f32_16x16x32_bf16 v[8:11], v[172:175], v[208:211], v[8:11]
	v_mfma_f32_16x16x32_bf16 v[12:15], v[164:167], v[208:211], v[12:15]
	v_mfma_f32_16x16x32_bf16 v[60:63], v[168:171], v[188:191], v[60:63]
	v_mfma_f32_16x16x32_bf16 v[56:59], v[180:183], v[188:191], v[56:59]
	v_mfma_f32_16x16x32_bf16 v[40:43], v[180:183], v[196:199], v[40:43]
	v_mfma_f32_16x16x32_bf16 v[44:47], v[168:171], v[196:199], v[44:47]
	v_mfma_f32_16x16x32_bf16 v[28:31], v[168:171], v[204:207], v[28:31]
	v_mfma_f32_16x16x32_bf16 v[24:27], v[180:183], v[204:207], v[24:27]
	v_mfma_f32_16x16x32_bf16 v[8:11], v[180:183], v[212:215], v[8:11]
	v_mfma_f32_16x16x32_bf16 v[12:15], v[168:171], v[212:215], v[12:15]
	s_barrier
	ds_read_b128 v[146:149], v132
	ds_read_b128 v[152:155], v132 offset:1024
	ds_read_b128 v[156:159], v132 offset:2048
	ds_read_b128 v[160:163], v132 offset:3072
	ds_read_b128 v[164:167], v133
	ds_read_b128 v[168:171], v133 offset:1024
	ds_read_b128 v[172:175], v133 offset:2048
	ds_read_b128 v[180:183], v133 offset:3072
	s_add_u32 s16, s28, 0x4000
	s_addc_u32 s17, s29, 0
	s_mov_b32 m0, s39
	ds_read_b128 v[184:187], v151 offset:32768
	ds_read_b128 v[188:191], v151 offset:33792
	ds_read_b128 v[192:195], v151 offset:34816
	ds_read_b128 v[196:199], v151 offset:35840
	ds_read_b128 v[200:203], v151 offset:36864
	ds_read_b128 v[204:207], v151 offset:37888
	ds_read_b128 v[208:211], v151 offset:38912
	ds_read_b128 v[212:215], v151 offset:39936
	global_load_lds_dwordx4 v134, s[16:17]
	s_mov_b32 m0, s56
	s_nop 0
	global_load_lds_dwordx4 v138, s[16:17]
	s_waitcnt vmcnt(8)
	s_waitcnt lgkmcnt(0)
	s_barrier
; #define PG8_BAR __builtin_amdgcn_s_barrier()
; template <class Epi, class Sched, bool ALIGN_EPI = false, bool SP2 = false>
; __device__ __forceinline__ void gemm_phase(PG8_LAS unsigned char* lds, const Gemm g, const Sched& S, const Epi& E) {
;     ...
;         if constexpr (Epi::PEEL) {
;             const char* a1 = cA + kstepA; const char* a2 = cA + 2 * kstepA; const char* b2 = cB + 2 * kstepB; const char* a3 = a2 + kstepA; const char* b3 = b2 + kstepB;
;             PG8_ITER(8);
;         }
;         for (int t = (Epi::PEEL ? 2 : 0); t < nt; t += 2) {
;             const bool last = (t == nt - 2);
;             const char* a1 = cA + (size_t)(t + 1) * kstepA;
;             const char* a2 = last ? nA : cA + (size_t)(t + 2) * kstepA; const char* b2 = last ? nB : cB + (size_t)(t + 2) * kstepB;
;             const char* a3 = a2 + kstepA; const char* b3 = b2 + kstepB;
;             PG8_ITER(8);
;         }
;     ...
;         if constexpr (ALIGN_EPI) { if (wr == 0) PG8_BAR; }
	s_waitcnt lgkmcnt(0)
	v_mfma_f32_16x16x32_bf16 v[118:121], v[146:149], v[184:187], v[118:121]
	v_mfma_f32_16x16x32_bf16 v[114:117], v[156:159], v[184:187], v[114:117]
	v_mfma_f32_16x16x32_bf16 v[98:101], v[156:159], v[192:195], v[98:101]
	v_mfma_f32_16x16x32_bf16 v[102:105], v[146:149], v[192:195], v[102:105]
	v_mfma_f32_16x16x32_bf16 v[84:87], v[146:149], v[200:203], v[84:87]
	v_mfma_f32_16x16x32_bf16 v[80:83], v[156:159], v[200:203], v[80:83]
	v_mfma_f32_16x16x32_bf16 v[64:67], v[156:159], v[208:211], v[64:67]
	v_mfma_f32_16x16x32_bf16 v[68:71], v[146:149], v[208:211], v[68:71]
	v_mfma_f32_16x16x32_bf16 v[118:121], v[152:155], v[188:191], v[118:121]
	v_mfma_f32_16x16x32_bf16 v[114:117], v[160:163], v[188:191], v[114:117]
	v_mfma_f32_16x16x32_bf16 v[98:101], v[160:163], v[196:199], v[98:101]
	v_mfma_f32_16x16x32_bf16 v[102:105], v[152:155], v[196:199], v[102:105]
	v_mfma_f32_16x16x32_bf16 v[84:87], v[152:155], v[204:207], v[84:87]
	v_mfma_f32_16x16x32_bf16 v[80:83], v[160:163], v[204:207], v[80:83]
	v_mfma_f32_16x16x32_bf16 v[64:67], v[160:163], v[212:215], v[64:67]
	v_mfma_f32_16x16x32_bf16 v[68:71], v[152:155], v[212:215], v[68:71]
	v_mfma_f32_16x16x32_bf16 v[126:129], v[164:167], v[184:187], v[126:129]
	v_mfma_f32_16x16x32_bf16 v[122:125], v[172:175], v[184:187], v[122:125]
	v_mfma_f32_16x16x32_bf16 v[106:109], v[172:175], v[192:195], v[106:109]
	v_mfma_f32_16x16x32_bf16 v[110:113], v[164:167], v[192:195], v[110:113]
	v_mfma_f32_16x16x32_bf16 v[92:95], v[164:167], v[200:203], v[92:95]
	v_mfma_f32_16x16x32_bf16 v[88:91], v[172:175], v[200:203], v[88:91]
	v_mfma_f32_16x16x32_bf16 v[72:75], v[172:175], v[208:211], v[72:75]
	v_mfma_f32_16x16x32_bf16 v[76:79], v[164:167], v[208:211], v[76:79]
	v_mfma_f32_16x16x32_bf16 v[126:129], v[168:171], v[188:191], v[126:129]
	v_mfma_f32_16x16x32_bf16 v[122:125], v[180:183], v[188:191], v[122:125]
	v_mfma_f32_16x16x32_bf16 v[106:109], v[180:183], v[196:199], v[106:109]
	v_mfma_f32_16x16x32_bf16 v[110:113], v[168:171], v[196:199], v[110:113]
	v_mfma_f32_16x16x32_bf16 v[92:95], v[168:171], v[204:207], v[92:95]
	v_mfma_f32_16x16x32_bf16 v[88:91], v[180:183], v[204:207], v[88:91]
	v_mfma_f32_16x16x32_bf16 v[72:75], v[180:183], v[212:215], v[72:75]
	v_mfma_f32_16x16x32_bf16 v[76:79], v[168:171], v[212:215], v[76:79]
	s_barrier
	s_mov_b32 m0, s31
	s_add_u32 s100, s44, 0x80
	s_addc_u32 s101, s45, 0
	s_add_u32 s16, s44, 0x40080
	ds_read_b128 v[184:187], v151 offset:49152
	ds_read_b128 v[188:191], v151 offset:50176
	ds_read_b128 v[192:195], v151 offset:51200
	ds_read_b128 v[196:199], v151 offset:52224
	ds_read_b128 v[200:203], v151 offset:53248
	ds_read_b128 v[204:207], v151 offset:54272
	ds_read_b128 v[208:211], v151 offset:55296
	ds_read_b128 v[212:215], v151 offset:56320
	global_load_lds_dwordx4 v136, s[100:101]
	s_mov_b32 m0, s12
	s_addc_u32 s17, s45, 0
	global_load_lds_dwordx4 v140, s[100:101]
	s_mov_b32 m0, s13
	s_nop 0
	global_load_lds_dwordx4 v136, s[16:17]
	s_mov_b32 m0, s11
	s_nop 0
	global_load_lds_dwordx4 v140, s[16:17]
	s_mov_b32 m0, s59
	s_nop 0
	global_load_lds_dwordx4 v134, s[42:43]
	s_mov_b32 m0, s96
	s_nop 0
	global_load_lds_dwordx4 v138, s[42:43]
	s_waitcnt vmcnt(8)
	s_waitcnt lgkmcnt(0)
	s_barrier
	s_waitcnt lgkmcnt(0)
	v_mfma_f32_16x16x32_bf16 v[52:55], v[146:149], v[184:187], v[52:55]
	v_mfma_f32_16x16x32_bf16 v[48:51], v[156:159], v[184:187], v[48:51]
	v_mfma_f32_16x16x32_bf16 v[32:35], v[156:159], v[192:195], v[32:35]
	v_mfma_f32_16x16x32_bf16 v[36:39], v[146:149], v[192:195], v[36:39]
	v_mfma_f32_16x16x32_bf16 v[20:23], v[146:149], v[200:203], v[20:23]
	v_mfma_f32_16x16x32_bf16 v[16:19], v[156:159], v[200:203], v[16:19]
	v_mfma_f32_16x16x32_bf16 v[0:3], v[156:159], v[208:211], v[0:3]
	v_mfma_f32_16x16x32_bf16 v[4:7], v[146:149], v[208:211], v[4:7]
	v_mfma_f32_16x16x32_bf16 v[52:55], v[152:155], v[188:191], v[52:55]
	v_mfma_f32_16x16x32_bf16 v[48:51], v[160:163], v[188:191], v[48:51]
	v_mfma_f32_16x16x32_bf16 v[32:35], v[160:163], v[196:199], v[32:35]
	v_mfma_f32_16x16x32_bf16 v[36:39], v[152:155], v[196:199], v[36:39]
	v_mfma_f32_16x16x32_bf16 v[20:23], v[152:155], v[204:207], v[20:23]
	v_mfma_f32_16x16x32_bf16 v[16:19], v[160:163], v[204:207], v[16:19]
	v_mfma_f32_16x16x32_bf16 v[0:3], v[160:163], v[212:215], v[0:3]
	v_mfma_f32_16x16x32_bf16 v[4:7], v[152:155], v[212:215], v[4:7]
	v_mfma_f32_16x16x32_bf16 v[60:63], v[164:167], v[184:187], v[60:63]
	v_mfma_f32_16x16x32_bf16 v[56:59], v[172:175], v[184:187], v[56:59]
	v_mfma_f32_16x16x32_bf16 v[40:43], v[172:175], v[192:195], v[40:43]
	v_mfma_f32_16x16x32_bf16 v[44:47], v[164:167], v[192:195], v[44:47]
	v_mfma_f32_16x16x32_bf16 v[28:31], v[164:167], v[200:203], v[28:31]
	v_mfma_f32_16x16x32_bf16 v[24:27], v[172:175], v[200:203], v[24:27]
	v_mfma_f32_16x16x32_bf16 v[8:11], v[172:175], v[208:211], v[8:11]
	v_mfma_f32_16x16x32_bf16 v[12:15], v[164:167], v[208:211], v[12:15]
	v_mfma_f32_16x16x32_bf16 v[60:63], v[168:171], v[188:191], v[60:63]
	v_mfma_f32_16x16x32_bf16 v[56:59], v[180:183], v[188:191], v[56:59]
	v_mfma_f32_16x16x32_bf16 v[40:43], v[180:183], v[196:199], v[40:43]
	v_mfma_f32_16x16x32_bf16 v[44:47], v[168:171], v[196:199], v[44:47]
	v_mfma_f32_16x16x32_bf16 v[28:31], v[168:171], v[204:207], v[28:31]
	v_mfma_f32_16x16x32_bf16 v[24:27], v[180:183], v[204:207], v[24:27]
	v_mfma_f32_16x16x32_bf16 v[8:11], v[180:183], v[212:215], v[8:11]
	v_mfma_f32_16x16x32_bf16 v[12:15], v[168:171], v[212:215], v[12:15]
	s_barrier
	s_add_i32 s18, s18, 2
	s_add_u32 s3, s3, 0x100
	s_addc_u32 s2, s2, 0
	s_add_u32 s24, s24, 0x800000
	s_addc_u32 s25, s25, 0
	s_cmp_gt_u32 s18, 13
	s_cbranch_scc0 .LBB0_250
	v_readlane_b32 s2, v255, 33
	v_readlane_b32 s3, v255, 34
	v_readlane_b32 s12, v255, 31
	s_and_b64 vcc, exec, s[2:3]
	v_readlane_b32 s13, v255, 32
	s_cbranch_vccz .LBB0_253
	s_barrier

.LBB0_345:
	s_add_i32 s10, s10, 2
	s_add_u32 s44, s42, s34
	s_addc_u32 s45, s43, s35
	s_add_i32 s18, 0, 0x10000
	s_and_b64 s[2:3], exec, s[46:47]
	s_cselect_b32 s3, s13, s59
	s_cselect_b32 s2, s12, s58
	s_add_i32 s38, 0, 0x14000
	v_add_u32_e32 v142, s18, v97
	v_add_u32_e32 v170, s38, v97
	ds_read_b128 v[122:125], v142
	ds_read_b128 v[126:129], v142 offset:1024
	ds_read_b128 v[138:141], v142 offset:2048
	ds_read_b128 v[142:145], v142 offset:3072
	ds_read_b128 v[146:149], v170
	ds_read_b128 v[150:153], v170 offset:1024
	ds_read_b128 v[154:157], v170 offset:2048
	ds_read_b128 v[170:173], v170 offset:3072
	s_add_i32 m0, s97, 0xc000
	ds_read_b128 v[174:177], v188
	ds_read_b128 v[180:183], v188 offset:1024
	ds_read_b128 v[184:187], v188 offset:2048
	ds_read_b128 v[190:193], v188 offset:3072
	ds_read_b128 v[194:197], v188 offset:4096
	ds_read_b128 v[198:201], v188 offset:5120
	ds_read_b128 v[202:205], v188 offset:6144
	ds_read_b128 v[206:209], v188 offset:7168
	global_load_lds_dwordx4 v168, s[24:25]
	s_add_i32 m0, s97, 0xe000
	s_nop 0
	global_load_lds_dwordx4 v166, s[24:25]
	s_waitcnt vmcnt(8)
	s_waitcnt lgkmcnt(0)
	s_barrier
	s_waitcnt lgkmcnt(0)
	v_mfma_f32_16x16x32_bf16 v[134:137], v[122:125], v[174:177], v[134:137]
	v_mfma_f32_16x16x32_bf16 v[130:133], v[138:141], v[174:177], v[130:133]
	v_mfma_f32_16x16x32_bf16 v[106:109], v[138:141], v[184:187], v[106:109]
	v_mfma_f32_16x16x32_bf16 v[110:113], v[122:125], v[184:187], v[110:113]
	v_mfma_f32_16x16x32_bf16 v[92:95], v[122:125], v[194:197], v[92:95]
	v_mfma_f32_16x16x32_bf16 v[88:91], v[138:141], v[194:197], v[88:91]
	v_mfma_f32_16x16x32_bf16 v[72:75], v[138:141], v[202:205], v[72:75]
	v_mfma_f32_16x16x32_bf16 v[76:79], v[122:125], v[202:205], v[76:79]
	v_mfma_f32_16x16x32_bf16 v[134:137], v[126:129], v[180:183], v[134:137]
	v_mfma_f32_16x16x32_bf16 v[130:133], v[142:145], v[180:183], v[130:133]
	v_mfma_f32_16x16x32_bf16 v[106:109], v[142:145], v[190:193], v[106:109]
	v_mfma_f32_16x16x32_bf16 v[110:113], v[126:129], v[190:193], v[110:113]
	v_mfma_f32_16x16x32_bf16 v[92:95], v[126:129], v[198:201], v[92:95]
	v_mfma_f32_16x16x32_bf16 v[88:91], v[142:145], v[198:201], v[88:91]
	v_mfma_f32_16x16x32_bf16 v[72:75], v[142:145], v[206:209], v[72:75]
	v_mfma_f32_16x16x32_bf16 v[76:79], v[126:129], v[206:209], v[76:79]
	v_mfma_f32_16x16x32_bf16 v[118:121], v[146:149], v[174:177], v[118:121]
	v_mfma_f32_16x16x32_bf16 v[114:117], v[154:157], v[174:177], v[114:117]
	v_mfma_f32_16x16x32_bf16 v[98:101], v[154:157], v[184:187], v[98:101]
	v_mfma_f32_16x16x32_bf16 v[102:105], v[146:149], v[184:187], v[102:105]
	v_mfma_f32_16x16x32_bf16 v[84:87], v[146:149], v[194:197], v[84:87]
	v_mfma_f32_16x16x32_bf16 v[80:83], v[154:157], v[194:197], v[80:83]
	v_mfma_f32_16x16x32_bf16 v[64:67], v[154:157], v[202:205], v[64:67]
	v_mfma_f32_16x16x32_bf16 v[68:71], v[146:149], v[202:205], v[68:71]
	v_mfma_f32_16x16x32_bf16 v[118:121], v[150:153], v[180:183], v[118:121]
	v_mfma_f32_16x16x32_bf16 v[114:117], v[170:173], v[180:183], v[114:117]
	v_mfma_f32_16x16x32_bf16 v[98:101], v[170:173], v[190:193], v[98:101]
	v_mfma_f32_16x16x32_bf16 v[102:105], v[150:153], v[190:193], v[102:105]
	v_mfma_f32_16x16x32_bf16 v[84:87], v[150:153], v[198:201], v[84:87]
	v_mfma_f32_16x16x32_bf16 v[80:83], v[170:173], v[198:201], v[80:83]
	v_mfma_f32_16x16x32_bf16 v[64:67], v[170:173], v[206:209], v[64:67]
	v_mfma_f32_16x16x32_bf16 v[68:71], v[150:153], v[206:209], v[68:71]
	s_barrier
	s_add_i32 s18, s18, s96
	v_lshl_add_u64 v[178:179], s[2:3], 0, v[162:163]
	s_mov_b32 m0, s18
	ds_read_b128 v[174:177], v188 offset:16384
	ds_read_b128 v[180:183], v188 offset:17408
	ds_read_b128 v[184:187], v188 offset:18432
	ds_read_b128 v[190:193], v188 offset:19456
	ds_read_b128 v[194:197], v188 offset:20480
	ds_read_b128 v[198:201], v188 offset:21504
	ds_read_b128 v[202:205], v188 offset:22528
	ds_read_b128 v[206:209], v188 offset:23552
	global_load_lds_dwordx4 v162, s[2:3]
	s_add_i32 m0, s18, 0x2000
	v_lshl_add_u64 v[210:211], s[2:3], 0, v[158:159]
	s_add_u32 s2, s2, s48
	s_addc_u32 s3, s3, 0
	s_add_i32 s18, s38, s96
	global_load_lds_dwordx4 v[210:211], off
	v_lshl_add_u64 v[212:213], s[2:3], 0, v[162:163]
	s_mov_b32 m0, s18
	v_lshl_add_u64 v[214:215], s[2:3], 0, v[158:159]
	global_load_lds_dwordx4 v162, s[2:3]
	s_add_i32 m0, s18, 0x2000
	s_nop 0
	global_load_lds_dwordx4 v158, s[2:3]
	s_mov_b32 m0, s97
	s_nop 0
	global_load_lds_dwordx4 v164, s[42:43]
	s_mov_b32 m0, s22
	s_nop 0
	global_load_lds_dwordx4 v160, s[42:43]
	s_waitcnt vmcnt(8)
	s_waitcnt lgkmcnt(0)
	s_barrier
	s_waitcnt lgkmcnt(0)
	v_mfma_f32_16x16x32_bf16 v[60:63], v[122:125], v[174:177], v[60:63]
	v_mfma_f32_16x16x32_bf16 v[56:59], v[138:141], v[174:177], v[56:59]
	v_mfma_f32_16x16x32_bf16 v[40:43], v[138:141], v[184:187], v[40:43]
	v_mfma_f32_16x16x32_bf16 v[44:47], v[122:125], v[184:187], v[44:47]
	v_mfma_f32_16x16x32_bf16 v[28:31], v[122:125], v[194:197], v[28:31]
	v_mfma_f32_16x16x32_bf16 v[24:27], v[138:141], v[194:197], v[24:27]
	v_mfma_f32_16x16x32_bf16 v[8:11], v[138:141], v[202:205], v[8:11]
	v_mfma_f32_16x16x32_bf16 v[12:15], v[122:125], v[202:205], v[12:15]
	v_mfma_f32_16x16x32_bf16 v[60:63], v[126:129], v[180:183], v[60:63]
	v_mfma_f32_16x16x32_bf16 v[56:59], v[142:145], v[180:183], v[56:59]
	v_mfma_f32_16x16x32_bf16 v[40:43], v[142:145], v[190:193], v[40:43]
	v_mfma_f32_16x16x32_bf16 v[44:47], v[126:129], v[190:193], v[44:47]
	v_mfma_f32_16x16x32_bf16 v[28:31], v[126:129], v[198:201], v[28:31]
	v_mfma_f32_16x16x32_bf16 v[24:27], v[142:145], v[198:201], v[24:27]
	v_mfma_f32_16x16x32_bf16 v[8:11], v[142:145], v[206:209], v[8:11]
	v_mfma_f32_16x16x32_bf16 v[12:15], v[126:129], v[206:209], v[12:15]
	v_mfma_f32_16x16x32_bf16 v[52:55], v[146:149], v[174:177], v[52:55]
	v_mfma_f32_16x16x32_bf16 v[48:51], v[154:157], v[174:177], v[48:51]
	v_mfma_f32_16x16x32_bf16 v[32:35], v[154:157], v[184:187], v[32:35]
	v_mfma_f32_16x16x32_bf16 v[36:39], v[146:149], v[184:187], v[36:39]
	v_mfma_f32_16x16x32_bf16 v[20:23], v[146:149], v[194:197], v[20:23]
	v_mfma_f32_16x16x32_bf16 v[16:19], v[154:157], v[194:197], v[16:19]
	v_mfma_f32_16x16x32_bf16 v[0:3], v[154:157], v[202:205], v[0:3]
	v_mfma_f32_16x16x32_bf16 v[4:7], v[146:149], v[202:205], v[4:7]
	v_mfma_f32_16x16x32_bf16 v[52:55], v[150:153], v[180:183], v[52:55]
	v_mfma_f32_16x16x32_bf16 v[48:51], v[170:173], v[180:183], v[48:51]
	v_mfma_f32_16x16x32_bf16 v[32:35], v[170:173], v[190:193], v[32:35]
	v_mfma_f32_16x16x32_bf16 v[36:39], v[150:153], v[190:193], v[36:39]
	v_mfma_f32_16x16x32_bf16 v[20:23], v[150:153], v[198:201], v[20:23]
	v_mfma_f32_16x16x32_bf16 v[16:19], v[170:173], v[198:201], v[16:19]
	v_mfma_f32_16x16x32_bf16 v[0:3], v[170:173], v[206:209], v[0:3]
	v_mfma_f32_16x16x32_bf16 v[4:7], v[150:153], v[206:209], v[4:7]
	s_barrier
	s_add_i32 s18, 0, 0x18000
	s_add_i32 s38, 0, 0x1c000
	v_add_u32_e32 v142, s18, v97
	v_add_u32_e32 v170, s38, v97
	ds_read_b128 v[122:125], v142
	ds_read_b128 v[126:129], v142 offset:1024
	ds_read_b128 v[138:141], v142 offset:2048
	ds_read_b128 v[142:145], v142 offset:3072
	ds_read_b128 v[146:149], v170
	ds_read_b128 v[150:153], v170 offset:1024
	ds_read_b128 v[154:157], v170 offset:2048
	ds_read_b128 v[170:173], v170 offset:3072
	s_add_u32 s2, s42, s98
	s_addc_u32 s3, s43, 0
	s_mov_b32 m0, s23
	ds_read_b128 v[174:177], v188 offset:32768
	ds_read_b128 v[180:183], v188 offset:33792
	ds_read_b128 v[184:187], v188 offset:34816
	ds_read_b128 v[190:193], v188 offset:35840
	ds_read_b128 v[194:197], v188 offset:36864
	ds_read_b128 v[198:201], v188 offset:37888
	ds_read_b128 v[202:205], v188 offset:38912
	ds_read_b128 v[206:209], v188 offset:39936
	global_load_lds_dwordx4 v164, s[2:3]
	s_mov_b32 m0, s19
	s_nop 0
	global_load_lds_dwordx4 v160, s[2:3]
	s_waitcnt vmcnt(8)
	s_waitcnt lgkmcnt(0)
	s_barrier
	s_waitcnt lgkmcnt(0)
	v_mfma_f32_16x16x32_bf16 v[134:137], v[122:125], v[174:177], v[134:137]
	v_mfma_f32_16x16x32_bf16 v[130:133], v[138:141], v[174:177], v[130:133]
	v_mfma_f32_16x16x32_bf16 v[106:109], v[138:141], v[184:187], v[106:109]
	v_mfma_f32_16x16x32_bf16 v[110:113], v[122:125], v[184:187], v[110:113]
	v_mfma_f32_16x16x32_bf16 v[92:95], v[122:125], v[194:197], v[92:95]
	v_mfma_f32_16x16x32_bf16 v[88:91], v[138:141], v[194:197], v[88:91]
	v_mfma_f32_16x16x32_bf16 v[72:75], v[138:141], v[202:205], v[72:75]
	v_mfma_f32_16x16x32_bf16 v[76:79], v[122:125], v[202:205], v[76:79]
	v_mfma_f32_16x16x32_bf16 v[134:137], v[126:129], v[180:183], v[134:137]
	v_mfma_f32_16x16x32_bf16 v[130:133], v[142:145], v[180:183], v[130:133]
	v_mfma_f32_16x16x32_bf16 v[106:109], v[142:145], v[190:193], v[106:109]
	v_mfma_f32_16x16x32_bf16 v[110:113], v[126:129], v[190:193], v[110:113]
	v_mfma_f32_16x16x32_bf16 v[92:95], v[126:129], v[198:201], v[92:95]
	v_mfma_f32_16x16x32_bf16 v[88:91], v[142:145], v[198:201], v[88:91]
	v_mfma_f32_16x16x32_bf16 v[72:75], v[142:145], v[206:209], v[72:75]
	v_mfma_f32_16x16x32_bf16 v[76:79], v[126:129], v[206:209], v[76:79]
	v_mfma_f32_16x16x32_bf16 v[118:121], v[146:149], v[174:177], v[118:121]
	v_mfma_f32_16x16x32_bf16 v[114:117], v[154:157], v[174:177], v[114:117]
	v_mfma_f32_16x16x32_bf16 v[98:101], v[154:157], v[184:187], v[98:101]
	v_mfma_f32_16x16x32_bf16 v[102:105], v[146:149], v[184:187], v[102:105]
	v_mfma_f32_16x16x32_bf16 v[84:87], v[146:149], v[194:197], v[84:87]
	v_mfma_f32_16x16x32_bf16 v[80:83], v[154:157], v[194:197], v[80:83]
	v_mfma_f32_16x16x32_bf16 v[64:67], v[154:157], v[202:205], v[64:67]
	v_mfma_f32_16x16x32_bf16 v[68:71], v[146:149], v[202:205], v[68:71]
	v_mfma_f32_16x16x32_bf16 v[118:121], v[150:153], v[180:183], v[118:121]
	v_mfma_f32_16x16x32_bf16 v[114:117], v[170:173], v[180:183], v[114:117]
	v_mfma_f32_16x16x32_bf16 v[98:101], v[170:173], v[190:193], v[98:101]
	v_mfma_f32_16x16x32_bf16 v[102:105], v[150:153], v[190:193], v[102:105]
	v_mfma_f32_16x16x32_bf16 v[84:87], v[150:153], v[198:201], v[84:87]
	v_mfma_f32_16x16x32_bf16 v[80:83], v[170:173], v[198:201], v[80:83]
	v_mfma_f32_16x16x32_bf16 v[64:67], v[170:173], v[206:209], v[64:67]
	v_mfma_f32_16x16x32_bf16 v[68:71], v[150:153], v[206:209], v[68:71]
	s_barrier
; template <class Epi, class Sched, bool ALIGN_EPI = false, bool SP2 = false>
; __device__ __forceinline__ void gemm_phase(PG8_LAS unsigned char* lds, const Gemm g, const Sched& S, const Epi& E) {
;     ...
;         if constexpr (Epi::PEEL) {
;             const char* a1 = cA + kstepA; const char* a2 = cA + 2 * kstepA; const char* b2 = cB + 2 * kstepB; const char* a3 = a2 + kstepA; const char* b3 = b2 + kstepB;
;             PG8_ITER(8);
;         }
;         for (int t = (Epi::PEEL ? 2 : 0); t < nt; t += 2) {
;             const bool last = (t == nt - 2);
;             const char* a1 = cA + (size_t)(t + 1) * kstepA;
;             const char* a2 = last ? nA : cA + (size_t)(t + 2) * kstepA; const char* b2 = last ? nB : cB + (size_t)(t + 2) * kstepB;
;             const char* a3 = a2 + kstepA; const char* b3 = b2 + kstepB;
;             PG8_ITER(8);
;         }
	s_add_i32 s2, s18, s96
	v_lshl_add_u64 v[178:179], v[178:179], 0, s[36:37]
	s_mov_b32 m0, s2
	ds_read_b128 v[174:177], v188 offset:49152
	ds_read_b128 v[180:183], v188 offset:50176
	ds_read_b128 v[184:187], v188 offset:51200
	ds_read_b128 v[190:193], v188 offset:52224
	ds_read_b128 v[194:197], v188 offset:53248
	ds_read_b128 v[198:201], v188 offset:54272
	ds_read_b128 v[202:205], v188 offset:55296
	ds_read_b128 v[206:209], v188 offset:56320
	global_load_lds_dwordx4 v[178:179], off
	v_lshl_add_u64 v[178:179], v[210:211], 0, s[36:37]
	s_add_i32 m0, s2, 0x2000
	s_add_i32 s2, s38, s96
	global_load_lds_dwordx4 v[178:179], off
	v_lshl_add_u64 v[178:179], v[212:213], 0, s[36:37]
	s_mov_b32 m0, s2
	s_nop 0
	global_load_lds_dwordx4 v[178:179], off
	v_lshl_add_u64 v[178:179], v[214:215], 0, s[36:37]
	s_add_i32 m0, s2, 0x2000
	s_nop 0
	global_load_lds_dwordx4 v[178:179], off
	s_mov_b32 m0, s6
	s_nop 0
	global_load_lds_dwordx4 v164, s[44:45]
	s_mov_b32 m0, s56
	s_nop 0
	global_load_lds_dwordx4 v160, s[44:45]
	s_waitcnt vmcnt(8)
	s_waitcnt lgkmcnt(0)
	s_barrier
	s_waitcnt lgkmcnt(0)
	v_mfma_f32_16x16x32_bf16 v[60:63], v[122:125], v[174:177], v[60:63]
	v_mfma_f32_16x16x32_bf16 v[56:59], v[138:141], v[174:177], v[56:59]
	v_mfma_f32_16x16x32_bf16 v[40:43], v[138:141], v[184:187], v[40:43]
	v_mfma_f32_16x16x32_bf16 v[44:47], v[122:125], v[184:187], v[44:47]
	v_mfma_f32_16x16x32_bf16 v[28:31], v[122:125], v[194:197], v[28:31]
	v_mfma_f32_16x16x32_bf16 v[24:27], v[138:141], v[194:197], v[24:27]
	v_mfma_f32_16x16x32_bf16 v[8:11], v[138:141], v[202:205], v[8:11]
	v_mfma_f32_16x16x32_bf16 v[12:15], v[122:125], v[202:205], v[12:15]
	v_mfma_f32_16x16x32_bf16 v[60:63], v[126:129], v[180:183], v[60:63]
	v_mfma_f32_16x16x32_bf16 v[56:59], v[142:145], v[180:183], v[56:59]
	v_mfma_f32_16x16x32_bf16 v[40:43], v[142:145], v[190:193], v[40:43]
	v_mfma_f32_16x16x32_bf16 v[44:47], v[126:129], v[190:193], v[44:47]
	v_mfma_f32_16x16x32_bf16 v[28:31], v[126:129], v[198:201], v[28:31]
	v_mfma_f32_16x16x32_bf16 v[24:27], v[142:145], v[198:201], v[24:27]
	v_mfma_f32_16x16x32_bf16 v[8:11], v[142:145], v[206:209], v[8:11]
	v_mfma_f32_16x16x32_bf16 v[12:15], v[126:129], v[206:209], v[12:15]
	v_mfma_f32_16x16x32_bf16 v[52:55], v[146:149], v[174:177], v[52:55]
	v_mfma_f32_16x16x32_bf16 v[48:51], v[154:157], v[174:177], v[48:51]
	v_mfma_f32_16x16x32_bf16 v[32:35], v[154:157], v[184:187], v[32:35]
	v_mfma_f32_16x16x32_bf16 v[36:39], v[146:149], v[184:187], v[36:39]
	v_mfma_f32_16x16x32_bf16 v[20:23], v[146:149], v[194:197], v[20:23]
	v_mfma_f32_16x16x32_bf16 v[16:19], v[154:157], v[194:197], v[16:19]
	v_mfma_f32_16x16x32_bf16 v[0:3], v[154:157], v[202:205], v[0:3]
	v_mfma_f32_16x16x32_bf16 v[4:7], v[146:149], v[202:205], v[4:7]
	v_mfma_f32_16x16x32_bf16 v[52:55], v[150:153], v[180:183], v[52:55]
	v_mfma_f32_16x16x32_bf16 v[48:51], v[170:173], v[180:183], v[48:51]
	v_mfma_f32_16x16x32_bf16 v[32:35], v[170:173], v[190:193], v[32:35]
	v_mfma_f32_16x16x32_bf16 v[36:39], v[150:153], v[190:193], v[36:39]
	v_mfma_f32_16x16x32_bf16 v[20:23], v[150:153], v[198:201], v[20:23]
	v_mfma_f32_16x16x32_bf16 v[16:19], v[170:173], v[198:201], v[16:19]
	v_mfma_f32_16x16x32_bf16 v[0:3], v[170:173], v[206:209], v[0:3]
	v_mfma_f32_16x16x32_bf16 v[4:7], v[150:153], v[206:209], v[4:7]
	s_barrier
	s_add_u32 s58, s58, 0x100
	s_addc_u32 s59, s59, 0
	s_add_u32 s24, s24, s49
	s_addc_u32 s25, s25, 0
	s_cmp_ge_u32 s10, s8
	s_cbranch_scc1 .LBB0_348

; template <class Epi, class Sched, bool ALIGN_EPI = false, bool SP2 = false>
; __device__ __forceinline__ void gemm_phase(PG8_LAS unsigned char* lds, const Gemm g, const Sched& S, const Epi& E) {
;     ...
;         const bool has_next = S.next(ui + 1, nxt);
;         const char* nA = has_next ? (const char*)g.A + (size_t)nxt.pm * tstepA : cA; const char* nB = has_next ? (const char*)g.Bt + (size_t)nxt.pn * tstepB : cB;
.LBB0_477:
	s_ashr_i32 s27, s26, 31
	s_lshl_b64 s[2:3], s[26:27], 15
	v_readlane_b32 s10, v255, 15
	s_add_u32 s28, s10, s2
	v_readlane_b32 s2, v255, 16
	s_addc_u32 s29, s2, s3
	s_ashr_i32 s25, s24, 31
	s_lshl_b64 s[2:3], s[24:25], 19
	s_add_u32 s30, s19, s2
	s_addc_u32 s31, s22, s3
	s_add_u32 s44, s34, 0x800000
	s_addc_u32 s45, s35, 0
	s_add_u32 s42, s34, 0xc00000
	s_addc_u32 s43, s35, 0
	s_add_i32 s61, 0, 0x10000
	s_and_b64 s[2:3], s[40:41], exec
	s_cselect_b32 s25, s29, s35
	s_cselect_b32 s27, s28, s34
	s_add_i32 s97, 0, 0x14000
	v_add_u32_e32 v142, s61, v97
	v_add_u32_e32 v143, s97, v97
	ds_read_b128 v[0:3], v142
	ds_read_b128 v[4:7], v142 offset:1024
	ds_read_b128 v[8:11], v142 offset:2048
	ds_read_b128 v[12:15], v142 offset:3072
	ds_read_b128 v[16:19], v143
	s_waitcnt lgkmcnt(0)
	ds_read_b128 v[20:23], v143 offset:1024
	ds_read_b128 v[24:27], v143 offset:2048
	ds_read_b128 v[28:31], v143 offset:3072
	s_and_b64 s[2:3], s[40:41], exec
	s_cselect_b32 s57, s31, s1
	s_cselect_b32 s58, s30, s0
	s_add_u32 s2, s34, 0x404000
	s_addc_u32 s3, s35, 0
	s_add_i32 s59, s23, 0xc000
	s_mov_b32 m0, s59
	s_add_i32 s60, s23, 0xe000
	ds_read_b128 v[32:35], v156
	ds_read_b128 v[36:39], v156 offset:1024
	ds_read_b128 v[40:43], v156 offset:2048
	ds_read_b128 v[44:47], v156 offset:3072
	ds_read_b128 v[48:51], v156 offset:4096
	ds_read_b128 v[52:55], v156 offset:5120
	ds_read_b128 v[56:59], v156 offset:6144
	ds_read_b128 v[60:63], v156 offset:7168
	global_load_lds_dwordx4 v130, s[2:3]
	s_mov_b32 m0, s60
	s_nop 0
	global_load_lds_dwordx4 v134, s[2:3]
	s_waitcnt vmcnt(8)
	s_waitcnt lgkmcnt(0)
	s_barrier
	s_waitcnt lgkmcnt(0)
	v_mfma_f32_16x16x32_bf16 v[88:91], v[0:3], v[56:59], 0
	v_mfma_f32_16x16x32_bf16 v[64:67], v[0:3], v[32:35], 0
	v_mfma_f32_16x16x32_bf16 v[68:71], v[8:11], v[32:35], 0
	v_mfma_f32_16x16x32_bf16 v[72:75], v[0:3], v[40:43], 0
	v_mfma_f32_16x16x32_bf16 v[76:79], v[8:11], v[40:43], 0
	v_mfma_f32_16x16x32_bf16 v[80:83], v[0:3], v[48:51], 0
	v_mfma_f32_16x16x32_bf16 v[84:87], v[8:11], v[48:51], 0
	v_mfma_f32_16x16x32_bf16 v[92:95], v[4:7], v[60:63], v[88:91]
	v_mfma_f32_16x16x32_bf16 v[88:91], v[8:11], v[56:59], 0
	v_mfma_f32_16x16x32_bf16 v[64:67], v[4:7], v[36:39], v[64:67]
	v_mfma_f32_16x16x32_bf16 v[68:71], v[12:15], v[36:39], v[68:71]
	v_mfma_f32_16x16x32_bf16 v[72:75], v[4:7], v[44:47], v[72:75]
	v_mfma_f32_16x16x32_bf16 v[76:79], v[12:15], v[44:47], v[76:79]
	v_mfma_f32_16x16x32_bf16 v[80:83], v[4:7], v[52:55], v[80:83]
	v_mfma_f32_16x16x32_bf16 v[84:87], v[12:15], v[52:55], v[84:87]
	v_mfma_f32_16x16x32_bf16 v[102:105], v[12:15], v[60:63], v[88:91]
	v_mfma_f32_16x16x32_bf16 v[88:91], v[16:19], v[32:35], 0
	v_mfma_f32_16x16x32_bf16 v[32:35], v[24:27], v[32:35], 0
	v_mfma_f32_16x16x32_bf16 v[110:113], v[20:23], v[36:39], v[88:91]
	v_mfma_f32_16x16x32_bf16 v[32:35], v[28:31], v[36:39], v[32:35]
	v_mfma_f32_16x16x32_bf16 v[36:39], v[16:19], v[40:43], 0
	v_mfma_f32_16x16x32_bf16 v[40:43], v[24:27], v[40:43], 0
	v_mfma_f32_16x16x32_bf16 v[36:39], v[20:23], v[44:47], v[36:39]
	v_mfma_f32_16x16x32_bf16 v[40:43], v[28:31], v[44:47], v[40:43]
	v_mfma_f32_16x16x32_bf16 v[44:47], v[16:19], v[48:51], 0
	v_mfma_f32_16x16x32_bf16 v[48:51], v[24:27], v[48:51], 0
	v_mfma_f32_16x16x32_bf16 v[44:47], v[20:23], v[52:55], v[44:47]
	v_mfma_f32_16x16x32_bf16 v[48:51], v[28:31], v[52:55], v[48:51]
	v_mfma_f32_16x16x32_bf16 v[52:55], v[16:19], v[56:59], 0
	v_mfma_f32_16x16x32_bf16 v[56:59], v[24:27], v[56:59], 0
	v_mfma_f32_16x16x32_bf16 v[52:55], v[20:23], v[60:63], v[52:55]
	v_mfma_f32_16x16x32_bf16 v[56:59], v[28:31], v[60:63], v[56:59]
	s_barrier
	v_lshl_add_u64 v[154:155], s[0:1], 0, v[132:133]
	s_mov_b64 s[2:3], 0x100
	s_add_i32 s61, s61, s9
	v_lshl_add_u64 v[144:145], v[154:155], 0, s[2:3]
	s_mov_b32 m0, s61
	v_lshl_add_u64 v[178:179], s[0:1], 0, v[136:137]
	s_add_i32 s96, s61, 0x2000
	ds_read_b128 v[60:63], v156 offset:16384
	ds_read_b128 v[88:91], v156 offset:17408
	ds_read_b128 v[98:101], v156 offset:18432
	ds_read_b128 v[106:109], v156 offset:19456
	ds_read_b128 v[114:117], v156 offset:20480
	ds_read_b128 v[118:121], v156 offset:21504
	ds_read_b128 v[122:125], v156 offset:22528
	ds_read_b128 v[126:129], v156 offset:23552
	global_load_lds_dwordx4 v[144:145], off
	v_lshl_add_u64 v[144:145], v[178:179], 0, s[2:3]
	s_add_u32 s2, s0, 0x40100
	s_mov_b32 m0, s96
	s_addc_u32 s3, s1, 0
	s_add_i32 s97, s97, s9
	global_load_lds_dwordx4 v[144:145], off
	s_mov_b32 m0, s97
	s_add_i32 s98, s97, 0x2000
	global_load_lds_dwordx4 v132, s[2:3]
	s_mov_b32 m0, s98
	s_nop 0
	global_load_lds_dwordx4 v136, s[2:3]
	s_mov_b32 m0, s23
	s_nop 0
	global_load_lds_dwordx4 v130, s[44:45]
	s_mov_b32 m0, s39
	s_nop 0
	global_load_lds_dwordx4 v134, s[44:45]
	s_waitcnt vmcnt(8)
	s_waitcnt lgkmcnt(0)
	s_barrier
	s_waitcnt lgkmcnt(0)
	v_mfma_f32_16x16x32_bf16 v[144:147], v[0:3], v[60:63], 0
	v_mfma_f32_16x16x32_bf16 v[158:161], v[0:3], v[98:101], 0
	v_mfma_f32_16x16x32_bf16 v[166:169], v[0:3], v[114:117], 0
	v_mfma_f32_16x16x32_bf16 v[0:3], v[0:3], v[122:125], 0
	v_mfma_f32_16x16x32_bf16 v[146:149], v[4:7], v[88:91], v[144:147]
	v_mfma_f32_16x16x32_bf16 v[158:161], v[4:7], v[106:109], v[158:161]
	v_mfma_f32_16x16x32_bf16 v[166:169], v[4:7], v[118:121], v[166:169]
	v_mfma_f32_16x16x32_bf16 v[0:3], v[4:7], v[126:129], v[0:3]
	v_mfma_f32_16x16x32_bf16 v[4:7], v[8:11], v[122:125], 0
	v_mfma_f32_16x16x32_bf16 v[150:153], v[8:11], v[60:63], 0
	v_mfma_f32_16x16x32_bf16 v[162:165], v[8:11], v[98:101], 0
	v_mfma_f32_16x16x32_bf16 v[170:173], v[8:11], v[114:117], 0
	v_mfma_f32_16x16x32_bf16 v[4:7], v[12:15], v[126:129], v[4:7]
	v_mfma_f32_16x16x32_bf16 v[150:153], v[12:15], v[88:91], v[150:153]
	v_mfma_f32_16x16x32_bf16 v[162:165], v[12:15], v[106:109], v[162:165]
	v_mfma_f32_16x16x32_bf16 v[170:173], v[12:15], v[118:121], v[170:173]
	v_mfma_f32_16x16x32_bf16 v[8:11], v[16:19], v[60:63], 0
	v_mfma_f32_16x16x32_bf16 v[12:15], v[20:23], v[88:91], v[8:11]
	v_mfma_f32_16x16x32_bf16 v[8:11], v[24:27], v[60:63], 0
	v_mfma_f32_16x16x32_bf16 v[174:177], v[28:31], v[88:91], v[8:11]
	v_mfma_f32_16x16x32_bf16 v[8:11], v[16:19], v[98:101], 0
	v_mfma_f32_16x16x32_bf16 v[188:191], v[20:23], v[106:109], v[8:11]
	v_mfma_f32_16x16x32_bf16 v[8:11], v[24:27], v[98:101], 0
	v_mfma_f32_16x16x32_bf16 v[192:195], v[28:31], v[106:109], v[8:11]
	v_mfma_f32_16x16x32_bf16 v[8:11], v[16:19], v[114:117], 0
	v_mfma_f32_16x16x32_bf16 v[196:199], v[20:23], v[118:121], v[8:11]
	v_mfma_f32_16x16x32_bf16 v[8:11], v[24:27], v[114:117], 0
	v_mfma_f32_16x16x32_bf16 v[200:203], v[28:31], v[118:121], v[8:11]
	v_mfma_f32_16x16x32_bf16 v[8:11], v[16:19], v[122:125], 0
	v_mfma_f32_16x16x32_bf16 v[204:207], v[20:23], v[126:129], v[8:11]
	v_mfma_f32_16x16x32_bf16 v[8:11], v[24:27], v[122:125], 0
	v_mfma_f32_16x16x32_bf16 v[208:211], v[28:31], v[126:129], v[8:11]
	s_barrier
	s_add_i32 s99, 0, 0x18000
	s_add_i32 vcc_hi, 0, 0x1c000
	v_add_u32_e32 v144, s99, v97
	v_add_u32_e32 v145, vcc_hi, v97
	s_nop 0
	ds_read_b128 v[8:11], v144
	ds_read_b128 v[20:23], v144 offset:1024
	ds_read_b128 v[28:31], v144 offset:2048
	ds_read_b128 v[212:215], v144 offset:3072
	ds_read_b128 v[216:219], v145
	ds_read_b128 v[220:223], v145 offset:1024
	ds_read_b128 v[234:237], v145 offset:2048
	ds_read_b128 v[238:241], v145 offset:3072
	s_add_u32 s2, s34, 0x804000
	s_addc_u32 s3, s35, 0
	s_mov_b32 m0, s46
	ds_read_b128 v[16:19], v156 offset:32768
	ds_read_b128 v[24:27], v156 offset:33792
	ds_read_b128 v[242:245], v156 offset:34816
	ds_read_b128 v[246:249], v156 offset:35840
	ds_read_b128 v[228:231], v156 offset:36864
	ds_read_b128 v[180:183], v156 offset:37888
	ds_read_b128 v[184:187], v156 offset:38912
	ds_read_b128 v[224:227], v156 offset:39936
	global_load_lds_dwordx4 v130, s[2:3]
	s_mov_b32 m0, s47
	s_nop 0
	global_load_lds_dwordx4 v134, s[2:3]
	s_waitcnt vmcnt(8)
	s_waitcnt lgkmcnt(0)
	s_barrier
	s_waitcnt lgkmcnt(0)
	v_mfma_f32_16x16x32_bf16 v[60:63], v[8:11], v[16:19], v[64:67]
	v_mfma_f32_16x16x32_bf16 v[122:125], v[20:23], v[24:27], v[60:63]
	v_mfma_f32_16x16x32_bf16 v[60:63], v[28:31], v[16:19], v[68:71]
	v_mfma_f32_16x16x32_bf16 v[114:117], v[212:215], v[24:27], v[60:63]
	v_mfma_f32_16x16x32_bf16 v[60:63], v[8:11], v[242:245], v[72:75]
	v_mfma_f32_16x16x32_bf16 v[106:109], v[20:23], v[246:249], v[60:63]
	v_mfma_f32_16x16x32_bf16 v[60:63], v[28:31], v[242:245], v[76:79]
	v_mfma_f32_16x16x32_bf16 v[98:101], v[212:215], v[246:249], v[60:63]
	v_mfma_f32_16x16x32_bf16 v[60:63], v[8:11], v[228:231], v[80:83]
	v_mfma_f32_16x16x32_bf16 v[88:91], v[20:23], v[180:183], v[60:63]
	v_mfma_f32_16x16x32_bf16 v[60:63], v[28:31], v[228:231], v[84:87]
	v_mfma_f32_16x16x32_bf16 v[80:83], v[212:215], v[180:183], v[60:63]
	v_mfma_f32_16x16x32_bf16 v[60:63], v[8:11], v[184:187], v[92:95]
	v_mfma_f32_16x16x32_bf16 v[72:75], v[20:23], v[224:227], v[60:63]
	v_mfma_f32_16x16x32_bf16 v[60:63], v[28:31], v[184:187], v[102:105]
	v_mfma_f32_16x16x32_bf16 v[60:63], v[212:215], v[224:227], v[60:63]
	v_mfma_f32_16x16x32_bf16 v[64:67], v[216:219], v[16:19], v[110:113]
	v_mfma_f32_16x16x32_bf16 v[16:19], v[234:237], v[16:19], v[32:35]
	v_mfma_f32_16x16x32_bf16 v[118:121], v[238:241], v[24:27], v[16:19]
	v_mfma_f32_16x16x32_bf16 v[16:19], v[216:219], v[242:245], v[36:39]
	v_mfma_f32_16x16x32_bf16 v[110:113], v[220:223], v[246:249], v[16:19]
	v_mfma_f32_16x16x32_bf16 v[16:19], v[234:237], v[242:245], v[40:43]
	v_mfma_f32_16x16x32_bf16 v[102:105], v[238:241], v[246:249], v[16:19]
	v_mfma_f32_16x16x32_bf16 v[16:19], v[216:219], v[228:231], v[44:47]
	v_mfma_f32_16x16x32_bf16 v[92:95], v[220:223], v[180:183], v[16:19]
	v_mfma_f32_16x16x32_bf16 v[16:19], v[234:237], v[228:231], v[48:51]
	v_mfma_f32_16x16x32_bf16 v[84:87], v[238:241], v[180:183], v[16:19]
	v_mfma_f32_16x16x32_bf16 v[16:19], v[216:219], v[184:187], v[52:55]
	v_mfma_f32_16x16x32_bf16 v[76:79], v[220:223], v[224:227], v[16:19]
	v_mfma_f32_16x16x32_bf16 v[16:19], v[234:237], v[184:187], v[56:59]
	v_mfma_f32_16x16x32_bf16 v[126:129], v[220:223], v[24:27], v[64:67]
	v_mfma_f32_16x16x32_bf16 v[68:71], v[238:241], v[224:227], v[16:19]
	s_barrier
; template <class Epi, class Sched, bool ALIGN_EPI = false, bool SP2 = false>
; __device__ __forceinline__ void gemm_phase(PG8_LAS unsigned char* lds, const Gemm g, const Sched& S, const Epi& E) {
;     ...
;             const bool last = (t == nt - 2);
;             const char* a1 = cA + (size_t)(t + 1) * kstepA;
;             const char* a2 = last ? nA : cA + (size_t)(t + 2) * kstepA; const char* b2 = last ? nB : cB + (size_t)(t + 2) * kstepB;
;             const char* a3 = a2 + kstepA; const char* b3 = b2 + kstepB;
	s_mov_b64 s[2:3], 0x180
	s_add_i32 s99, s99, s9
	s_nop 1
	v_lshl_add_u64 v[16:17], v[154:155], 0, s[2:3]
	s_mov_b32 m0, s99
	s_add_i32 vcc_lo, s99, 0x2000
	ds_read_b128 v[36:39], v156 offset:49152
	ds_read_b128 v[44:47], v156 offset:50176
	ds_read_b128 v[180:183], v156 offset:51200
	ds_read_b128 v[184:187], v156 offset:52224
	ds_read_b128 v[224:227], v156 offset:53248
	ds_read_b128 v[228:231], v156 offset:54272
	ds_read_b128 v[242:245], v156 offset:55296
	ds_read_b128 v[246:249], v156 offset:56320
	global_load_lds_dwordx4 v[16:17], off
	v_lshl_add_u64 v[16:17], v[178:179], 0, s[2:3]
	s_add_u32 s2, s0, 0x40180
	s_mov_b32 m0, vcc_lo
	s_addc_u32 s3, s1, 0
	s_add_i32 vcc_hi, vcc_hi, s9
	global_load_lds_dwordx4 v[16:17], off
	s_mov_b32 m0, vcc_hi
	s_add_i32 s38, vcc_hi, 0x2000
	global_load_lds_dwordx4 v132, s[2:3]
	s_mov_b32 m0, s38
	s_nop 0
	global_load_lds_dwordx4 v136, s[2:3]
	s_mov_b32 m0, s49
	s_nop 0
	global_load_lds_dwordx4 v130, s[42:43]
	s_mov_b32 m0, s50
	s_nop 0
	global_load_lds_dwordx4 v134, s[42:43]
	s_waitcnt vmcnt(8)
	s_waitcnt lgkmcnt(0)
	s_barrier
	s_waitcnt lgkmcnt(0)
	v_mfma_f32_16x16x32_bf16 v[16:19], v[8:11], v[36:39], v[146:149]
	v_mfma_f32_16x16x32_bf16 v[56:59], v[20:23], v[44:47], v[16:19]
	v_mfma_f32_16x16x32_bf16 v[16:19], v[28:31], v[36:39], v[150:153]
	v_mfma_f32_16x16x32_bf16 v[48:51], v[212:215], v[44:47], v[16:19]
	v_mfma_f32_16x16x32_bf16 v[16:19], v[8:11], v[180:183], v[158:161]
	v_mfma_f32_16x16x32_bf16 v[40:43], v[20:23], v[184:187], v[16:19]
	v_mfma_f32_16x16x32_bf16 v[16:19], v[28:31], v[180:183], v[162:165]
	v_mfma_f32_16x16x32_bf16 v[32:35], v[212:215], v[184:187], v[16:19]
	v_mfma_f32_16x16x32_bf16 v[16:19], v[8:11], v[224:227], v[166:169]
	v_mfma_f32_16x16x32_bf16 v[0:3], v[8:11], v[242:245], v[0:3]
	v_mfma_f32_16x16x32_bf16 v[24:27], v[20:23], v[228:231], v[16:19]
	v_mfma_f32_16x16x32_bf16 v[16:19], v[28:31], v[224:227], v[170:173]
	v_mfma_f32_16x16x32_bf16 v[8:11], v[20:23], v[246:249], v[0:3]
	v_mfma_f32_16x16x32_bf16 v[0:3], v[28:31], v[242:245], v[4:7]
	v_mfma_f32_16x16x32_bf16 v[16:19], v[212:215], v[228:231], v[16:19]
	v_mfma_f32_16x16x32_bf16 v[0:3], v[212:215], v[246:249], v[0:3]
	v_mfma_f32_16x16x32_bf16 v[4:7], v[216:219], v[36:39], v[12:15]
	v_mfma_f32_16x16x32_bf16 v[64:67], v[220:223], v[44:47], v[4:7]
	v_mfma_f32_16x16x32_bf16 v[4:7], v[234:237], v[36:39], v[174:177]
	v_mfma_f32_16x16x32_bf16 v[52:55], v[238:241], v[44:47], v[4:7]
	v_mfma_f32_16x16x32_bf16 v[4:7], v[216:219], v[180:183], v[188:191]
	v_mfma_f32_16x16x32_bf16 v[44:47], v[220:223], v[184:187], v[4:7]
	v_mfma_f32_16x16x32_bf16 v[4:7], v[234:237], v[180:183], v[192:195]
	v_mfma_f32_16x16x32_bf16 v[36:39], v[238:241], v[184:187], v[4:7]
	v_mfma_f32_16x16x32_bf16 v[4:7], v[216:219], v[224:227], v[196:199]
	v_mfma_f32_16x16x32_bf16 v[28:31], v[220:223], v[228:231], v[4:7]
	v_mfma_f32_16x16x32_bf16 v[4:7], v[234:237], v[224:227], v[200:203]
	v_mfma_f32_16x16x32_bf16 v[20:23], v[238:241], v[228:231], v[4:7]
	v_mfma_f32_16x16x32_bf16 v[4:7], v[216:219], v[242:245], v[204:207]
	v_mfma_f32_16x16x32_bf16 v[12:15], v[220:223], v[246:249], v[4:7]
	v_mfma_f32_16x16x32_bf16 v[4:7], v[234:237], v[242:245], v[208:211]
	v_mfma_f32_16x16x32_bf16 v[4:7], v[238:241], v[246:249], v[4:7]
	s_barrier
	s_add_u32 s3, s0, 0x200
	s_addc_u32 s2, s1, 0
	s_add_u32 s0, s34, 0xc04000
	s_addc_u32 s1, s35, 0
	s_mov_b32 s18, 0
.LBB0_478:
	ds_read_b128 v[146:149], v142
	ds_read_b128 v[150:153], v142 offset:1024
	ds_read_b128 v[158:161], v142 offset:2048
	ds_read_b128 v[162:165], v142 offset:3072
	ds_read_b128 v[166:169], v143
	ds_read_b128 v[170:173], v143 offset:1024
	ds_read_b128 v[174:177], v143 offset:2048
	ds_read_b128 v[180:183], v143 offset:3072
	s_add_u32 s10, s0, 0x3fc000
	s_addc_u32 s11, s1, 0
	s_cmp_eq_u32 s18, 12
	s_cselect_b32 s44, s27, s10
	s_cselect_b32 s45, s25, s11
	s_cselect_b32 s42, s58, s3
	s_cselect_b32 s43, s57, s2
	s_add_u32 s34, s44, 0x400000
	s_addc_u32 s35, s45, 0
	s_mov_b32 m0, s59
	ds_read_b128 v[184:187], v156
	ds_read_b128 v[188:191], v156 offset:1024
	ds_read_b128 v[192:195], v156 offset:2048
	ds_read_b128 v[196:199], v156 offset:3072
	ds_read_b128 v[200:203], v156 offset:4096
	ds_read_b128 v[204:207], v156 offset:5120
	ds_read_b128 v[208:211], v156 offset:6144
	ds_read_b128 v[212:215], v156 offset:7168
	global_load_lds_dwordx4 v140, s[0:1]
	s_mov_b32 m0, s60
	s_nop 0
	global_load_lds_dwordx4 v138, s[0:1]
	s_waitcnt vmcnt(8)
	s_waitcnt lgkmcnt(0)
	s_barrier
	s_waitcnt lgkmcnt(0)
	v_mfma_f32_16x16x32_bf16 v[122:125], v[146:149], v[184:187], v[122:125]
	v_mfma_f32_16x16x32_bf16 v[114:117], v[158:161], v[184:187], v[114:117]
	v_mfma_f32_16x16x32_bf16 v[98:101], v[158:161], v[192:195], v[98:101]
	v_mfma_f32_16x16x32_bf16 v[106:109], v[146:149], v[192:195], v[106:109]
	v_mfma_f32_16x16x32_bf16 v[88:91], v[146:149], v[200:203], v[88:91]
	v_mfma_f32_16x16x32_bf16 v[80:83], v[158:161], v[200:203], v[80:83]
	v_mfma_f32_16x16x32_bf16 v[60:63], v[158:161], v[208:211], v[60:63]
	v_mfma_f32_16x16x32_bf16 v[72:75], v[146:149], v[208:211], v[72:75]
	v_mfma_f32_16x16x32_bf16 v[122:125], v[150:153], v[188:191], v[122:125]
	v_mfma_f32_16x16x32_bf16 v[114:117], v[162:165], v[188:191], v[114:117]
	v_mfma_f32_16x16x32_bf16 v[98:101], v[162:165], v[196:199], v[98:101]
	v_mfma_f32_16x16x32_bf16 v[106:109], v[150:153], v[196:199], v[106:109]
	v_mfma_f32_16x16x32_bf16 v[88:91], v[150:153], v[204:207], v[88:91]
	v_mfma_f32_16x16x32_bf16 v[80:83], v[162:165], v[204:207], v[80:83]
	v_mfma_f32_16x16x32_bf16 v[60:63], v[162:165], v[212:215], v[60:63]
	v_mfma_f32_16x16x32_bf16 v[72:75], v[150:153], v[212:215], v[72:75]
	v_mfma_f32_16x16x32_bf16 v[126:129], v[166:169], v[184:187], v[126:129]
	v_mfma_f32_16x16x32_bf16 v[118:121], v[174:177], v[184:187], v[118:121]
	v_mfma_f32_16x16x32_bf16 v[102:105], v[174:177], v[192:195], v[102:105]
	v_mfma_f32_16x16x32_bf16 v[110:113], v[166:169], v[192:195], v[110:113]
	v_mfma_f32_16x16x32_bf16 v[92:95], v[166:169], v[200:203], v[92:95]
	v_mfma_f32_16x16x32_bf16 v[84:87], v[174:177], v[200:203], v[84:87]
	v_mfma_f32_16x16x32_bf16 v[68:71], v[174:177], v[208:211], v[68:71]
	v_mfma_f32_16x16x32_bf16 v[76:79], v[166:169], v[208:211], v[76:79]
	v_mfma_f32_16x16x32_bf16 v[126:129], v[170:173], v[188:191], v[126:129]
	v_mfma_f32_16x16x32_bf16 v[118:121], v[180:183], v[188:191], v[118:121]
	v_mfma_f32_16x16x32_bf16 v[102:105], v[180:183], v[196:199], v[102:105]
	v_mfma_f32_16x16x32_bf16 v[110:113], v[170:173], v[196:199], v[110:113]
	v_mfma_f32_16x16x32_bf16 v[92:95], v[170:173], v[204:207], v[92:95]
	v_mfma_f32_16x16x32_bf16 v[84:87], v[180:183], v[204:207], v[84:87]
	v_mfma_f32_16x16x32_bf16 v[68:71], v[180:183], v[212:215], v[68:71]
	v_mfma_f32_16x16x32_bf16 v[76:79], v[170:173], v[212:215], v[76:79]
	s_barrier
	s_mov_b32 m0, s61
	s_add_u32 s10, s42, 0x40000
	ds_read_b128 v[184:187], v156 offset:16384
	ds_read_b128 v[188:191], v156 offset:17408
	ds_read_b128 v[192:195], v156 offset:18432
	ds_read_b128 v[196:199], v156 offset:19456
	ds_read_b128 v[200:203], v156 offset:20480
	ds_read_b128 v[204:207], v156 offset:21504
	ds_read_b128 v[208:211], v156 offset:22528
	ds_read_b128 v[212:215], v156 offset:23552
	global_load_lds_dwordx4 v132, s[42:43]
	s_mov_b32 m0, s96
	s_addc_u32 s11, s43, 0
	global_load_lds_dwordx4 v136, s[42:43]
	s_mov_b32 m0, s97
	s_nop 0
	global_load_lds_dwordx4 v132, s[10:11]
	s_mov_b32 m0, s98
	s_nop 0
	global_load_lds_dwordx4 v136, s[10:11]
	s_mov_b32 m0, s23
	s_nop 0
	global_load_lds_dwordx4 v130, s[44:45]
	s_mov_b32 m0, s39
	s_nop 0
	global_load_lds_dwordx4 v134, s[44:45]
	s_waitcnt vmcnt(8)
	s_waitcnt lgkmcnt(0)
	s_barrier
	s_waitcnt lgkmcnt(0)
	v_mfma_f32_16x16x32_bf16 v[56:59], v[146:149], v[184:187], v[56:59]
	v_mfma_f32_16x16x32_bf16 v[48:51], v[158:161], v[184:187], v[48:51]
	v_mfma_f32_16x16x32_bf16 v[32:35], v[158:161], v[192:195], v[32:35]
	v_mfma_f32_16x16x32_bf16 v[40:43], v[146:149], v[192:195], v[40:43]
	v_mfma_f32_16x16x32_bf16 v[24:27], v[146:149], v[200:203], v[24:27]
	v_mfma_f32_16x16x32_bf16 v[16:19], v[158:161], v[200:203], v[16:19]
	v_mfma_f32_16x16x32_bf16 v[0:3], v[158:161], v[208:211], v[0:3]
	v_mfma_f32_16x16x32_bf16 v[8:11], v[146:149], v[208:211], v[8:11]
	v_mfma_f32_16x16x32_bf16 v[56:59], v[150:153], v[188:191], v[56:59]
	v_mfma_f32_16x16x32_bf16 v[48:51], v[162:165], v[188:191], v[48:51]
	v_mfma_f32_16x16x32_bf16 v[32:35], v[162:165], v[196:199], v[32:35]
	v_mfma_f32_16x16x32_bf16 v[40:43], v[150:153], v[196:199], v[40:43]
	v_mfma_f32_16x16x32_bf16 v[24:27], v[150:153], v[204:207], v[24:27]
	v_mfma_f32_16x16x32_bf16 v[16:19], v[162:165], v[204:207], v[16:19]
	v_mfma_f32_16x16x32_bf16 v[0:3], v[162:165], v[212:215], v[0:3]
	v_mfma_f32_16x16x32_bf16 v[8:11], v[150:153], v[212:215], v[8:11]
	v_mfma_f32_16x16x32_bf16 v[64:67], v[166:169], v[184:187], v[64:67]
	v_mfma_f32_16x16x32_bf16 v[52:55], v[174:177], v[184:187], v[52:55]
	v_mfma_f32_16x16x32_bf16 v[36:39], v[174:177], v[192:195], v[36:39]
	v_mfma_f32_16x16x32_bf16 v[44:47], v[166:169], v[192:195], v[44:47]
	v_mfma_f32_16x16x32_bf16 v[28:31], v[166:169], v[200:203], v[28:31]
	v_mfma_f32_16x16x32_bf16 v[20:23], v[174:177], v[200:203], v[20:23]
	v_mfma_f32_16x16x32_bf16 v[4:7], v[174:177], v[208:211], v[4:7]
	v_mfma_f32_16x16x32_bf16 v[12:15], v[166:169], v[208:211], v[12:15]
	v_mfma_f32_16x16x32_bf16 v[64:67], v[170:173], v[188:191], v[64:67]
	v_mfma_f32_16x16x32_bf16 v[52:55], v[180:183], v[188:191], v[52:55]
	v_mfma_f32_16x16x32_bf16 v[36:39], v[180:183], v[196:199], v[36:39]
	v_mfma_f32_16x16x32_bf16 v[44:47], v[170:173], v[196:199], v[44:47]
	v_mfma_f32_16x16x32_bf16 v[28:31], v[170:173], v[204:207], v[28:31]
	v_mfma_f32_16x16x32_bf16 v[20:23], v[180:183], v[204:207], v[20:23]
	v_mfma_f32_16x16x32_bf16 v[4:7], v[180:183], v[212:215], v[4:7]
	v_mfma_f32_16x16x32_bf16 v[12:15], v[170:173], v[212:215], v[12:15]
	s_barrier
	ds_read_b128 v[146:149], v144
	ds_read_b128 v[150:153], v144 offset:1024
	ds_read_b128 v[158:161], v144 offset:2048
	ds_read_b128 v[162:165], v144 offset:3072
	ds_read_b128 v[166:169], v145
	ds_read_b128 v[170:173], v145 offset:1024
	ds_read_b128 v[174:177], v145 offset:2048
	ds_read_b128 v[180:183], v145 offset:3072
	s_add_u32 s10, s44, 0x4000
	s_addc_u32 s11, s45, 0
	s_mov_b32 m0, s46
	ds_read_b128 v[184:187], v156 offset:32768
	ds_read_b128 v[188:191], v156 offset:33792
	ds_read_b128 v[192:195], v156 offset:34816
	ds_read_b128 v[196:199], v156 offset:35840
	ds_read_b128 v[200:203], v156 offset:36864
	ds_read_b128 v[204:207], v156 offset:37888
	ds_read_b128 v[208:211], v156 offset:38912
	ds_read_b128 v[212:215], v156 offset:39936
	global_load_lds_dwordx4 v130, s[10:11]
	s_mov_b32 m0, s47
	s_nop 0
	global_load_lds_dwordx4 v134, s[10:11]
	s_waitcnt vmcnt(8)
	s_waitcnt lgkmcnt(0)
	s_barrier
; template <class Epi, class Sched, bool ALIGN_EPI = false, bool SP2 = false>
; __device__ __forceinline__ void gemm_phase(PG8_LAS unsigned char* lds, const Gemm g, const Sched& S, const Epi& E) {
;     ...
;         for (int t = (Epi::PEEL ? 2 : 0); t < nt; t += 2) {
;             const bool last = (t == nt - 2);
;             const char* a1 = cA + (size_t)(t + 1) * kstepA;
;             const char* a2 = last ? nA : cA + (size_t)(t + 2) * kstepA; const char* b2 = last ? nB : cB + (size_t)(t + 2) * kstepB;
;             const char* a3 = a2 + kstepA; const char* b3 = b2 + kstepB;
;             PG8_ITER(8);
;         }
	s_waitcnt lgkmcnt(0)
	v_mfma_f32_16x16x32_bf16 v[122:125], v[146:149], v[184:187], v[122:125]
	v_mfma_f32_16x16x32_bf16 v[114:117], v[158:161], v[184:187], v[114:117]
	v_mfma_f32_16x16x32_bf16 v[98:101], v[158:161], v[192:195], v[98:101]
	v_mfma_f32_16x16x32_bf16 v[106:109], v[146:149], v[192:195], v[106:109]
	v_mfma_f32_16x16x32_bf16 v[88:91], v[146:149], v[200:203], v[88:91]
	v_mfma_f32_16x16x32_bf16 v[80:83], v[158:161], v[200:203], v[80:83]
	v_mfma_f32_16x16x32_bf16 v[60:63], v[158:161], v[208:211], v[60:63]
	v_mfma_f32_16x16x32_bf16 v[72:75], v[146:149], v[208:211], v[72:75]
	v_mfma_f32_16x16x32_bf16 v[122:125], v[150:153], v[188:191], v[122:125]
	v_mfma_f32_16x16x32_bf16 v[114:117], v[162:165], v[188:191], v[114:117]
	v_mfma_f32_16x16x32_bf16 v[98:101], v[162:165], v[196:199], v[98:101]
	v_mfma_f32_16x16x32_bf16 v[106:109], v[150:153], v[196:199], v[106:109]
	v_mfma_f32_16x16x32_bf16 v[88:91], v[150:153], v[204:207], v[88:91]
	v_mfma_f32_16x16x32_bf16 v[80:83], v[162:165], v[204:207], v[80:83]
	v_mfma_f32_16x16x32_bf16 v[60:63], v[162:165], v[212:215], v[60:63]
	v_mfma_f32_16x16x32_bf16 v[72:75], v[150:153], v[212:215], v[72:75]
	v_mfma_f32_16x16x32_bf16 v[126:129], v[166:169], v[184:187], v[126:129]
	v_mfma_f32_16x16x32_bf16 v[118:121], v[174:177], v[184:187], v[118:121]
	v_mfma_f32_16x16x32_bf16 v[102:105], v[174:177], v[192:195], v[102:105]
	v_mfma_f32_16x16x32_bf16 v[110:113], v[166:169], v[192:195], v[110:113]
	v_mfma_f32_16x16x32_bf16 v[92:95], v[166:169], v[200:203], v[92:95]
	v_mfma_f32_16x16x32_bf16 v[84:87], v[174:177], v[200:203], v[84:87]
	v_mfma_f32_16x16x32_bf16 v[68:71], v[174:177], v[208:211], v[68:71]
	v_mfma_f32_16x16x32_bf16 v[76:79], v[166:169], v[208:211], v[76:79]
	v_mfma_f32_16x16x32_bf16 v[126:129], v[170:173], v[188:191], v[126:129]
	v_mfma_f32_16x16x32_bf16 v[118:121], v[180:183], v[188:191], v[118:121]
	v_mfma_f32_16x16x32_bf16 v[102:105], v[180:183], v[196:199], v[102:105]
	v_mfma_f32_16x16x32_bf16 v[110:113], v[170:173], v[196:199], v[110:113]
	v_mfma_f32_16x16x32_bf16 v[92:95], v[170:173], v[204:207], v[92:95]
	v_mfma_f32_16x16x32_bf16 v[84:87], v[180:183], v[204:207], v[84:87]
	v_mfma_f32_16x16x32_bf16 v[68:71], v[180:183], v[212:215], v[68:71]
	v_mfma_f32_16x16x32_bf16 v[76:79], v[170:173], v[212:215], v[76:79]
	s_barrier
	s_mov_b32 m0, s99
	s_add_u32 s100, s42, 0x80
	s_addc_u32 s101, s43, 0
	s_add_u32 s10, s42, 0x40080
	ds_read_b128 v[184:187], v156 offset:49152
	ds_read_b128 v[188:191], v156 offset:50176
	ds_read_b128 v[192:195], v156 offset:51200
	ds_read_b128 v[196:199], v156 offset:52224
	ds_read_b128 v[200:203], v156 offset:53248
	ds_read_b128 v[204:207], v156 offset:54272
	ds_read_b128 v[208:211], v156 offset:55296
	ds_read_b128 v[212:215], v156 offset:56320
	global_load_lds_dwordx4 v132, s[100:101]
	s_mov_b32 m0, vcc_lo
	s_addc_u32 s11, s43, 0
	global_load_lds_dwordx4 v136, s[100:101]
	s_mov_b32 m0, vcc_hi
	s_nop 0
	global_load_lds_dwordx4 v132, s[10:11]
	s_mov_b32 m0, s38
	s_nop 0
	global_load_lds_dwordx4 v136, s[10:11]
	s_mov_b32 m0, s49
	s_nop 0
	global_load_lds_dwordx4 v130, s[34:35]
	s_mov_b32 m0, s50
	s_nop 0
	global_load_lds_dwordx4 v134, s[34:35]
	s_waitcnt vmcnt(8)
	s_waitcnt lgkmcnt(0)
	s_barrier
	s_waitcnt lgkmcnt(0)
	v_mfma_f32_16x16x32_bf16 v[56:59], v[146:149], v[184:187], v[56:59]
	v_mfma_f32_16x16x32_bf16 v[48:51], v[158:161], v[184:187], v[48:51]
	v_mfma_f32_16x16x32_bf16 v[32:35], v[158:161], v[192:195], v[32:35]
	v_mfma_f32_16x16x32_bf16 v[40:43], v[146:149], v[192:195], v[40:43]
	v_mfma_f32_16x16x32_bf16 v[24:27], v[146:149], v[200:203], v[24:27]
	v_mfma_f32_16x16x32_bf16 v[16:19], v[158:161], v[200:203], v[16:19]
	v_mfma_f32_16x16x32_bf16 v[0:3], v[158:161], v[208:211], v[0:3]
	v_mfma_f32_16x16x32_bf16 v[8:11], v[146:149], v[208:211], v[8:11]
	v_mfma_f32_16x16x32_bf16 v[56:59], v[150:153], v[188:191], v[56:59]
	v_mfma_f32_16x16x32_bf16 v[48:51], v[162:165], v[188:191], v[48:51]
	v_mfma_f32_16x16x32_bf16 v[32:35], v[162:165], v[196:199], v[32:35]
	v_mfma_f32_16x16x32_bf16 v[40:43], v[150:153], v[196:199], v[40:43]
	v_mfma_f32_16x16x32_bf16 v[24:27], v[150:153], v[204:207], v[24:27]
	v_mfma_f32_16x16x32_bf16 v[16:19], v[162:165], v[204:207], v[16:19]
	v_mfma_f32_16x16x32_bf16 v[0:3], v[162:165], v[212:215], v[0:3]
	v_mfma_f32_16x16x32_bf16 v[8:11], v[150:153], v[212:215], v[8:11]
	v_mfma_f32_16x16x32_bf16 v[64:67], v[166:169], v[184:187], v[64:67]
	v_mfma_f32_16x16x32_bf16 v[52:55], v[174:177], v[184:187], v[52:55]
	v_mfma_f32_16x16x32_bf16 v[36:39], v[174:177], v[192:195], v[36:39]
	v_mfma_f32_16x16x32_bf16 v[44:47], v[166:169], v[192:195], v[44:47]
	v_mfma_f32_16x16x32_bf16 v[28:31], v[166:169], v[200:203], v[28:31]
	v_mfma_f32_16x16x32_bf16 v[20:23], v[174:177], v[200:203], v[20:23]
	v_mfma_f32_16x16x32_bf16 v[4:7], v[174:177], v[208:211], v[4:7]
	v_mfma_f32_16x16x32_bf16 v[12:15], v[166:169], v[208:211], v[12:15]
	v_mfma_f32_16x16x32_bf16 v[64:67], v[170:173], v[188:191], v[64:67]
	v_mfma_f32_16x16x32_bf16 v[52:55], v[180:183], v[188:191], v[52:55]
	v_mfma_f32_16x16x32_bf16 v[36:39], v[180:183], v[196:199], v[36:39]
	v_mfma_f32_16x16x32_bf16 v[44:47], v[170:173], v[196:199], v[44:47]
	v_mfma_f32_16x16x32_bf16 v[28:31], v[170:173], v[204:207], v[28:31]
	v_mfma_f32_16x16x32_bf16 v[20:23], v[180:183], v[204:207], v[20:23]
	v_mfma_f32_16x16x32_bf16 v[4:7], v[180:183], v[212:215], v[4:7]
	v_mfma_f32_16x16x32_bf16 v[12:15], v[170:173], v[212:215], v[12:15]
	s_barrier
	s_add_i32 s18, s18, 2
	s_add_u32 s3, s3, 0x100
	s_addc_u32 s2, s2, 0
	s_add_u32 s0, s0, 0x800000
	s_addc_u32 s1, s1, 0
	s_cmp_gt_u32 s18, 13
	s_cbranch_scc0 .LBB0_478
	s_and_b64 vcc, exec, s[16:17]
	s_cbranch_vccz .LBB0_481
	s_barrier
